# K-loops: all fragment ds_reads issued first in every load segment, LDS-DMA after (dependency-checked reorder)
# speedup vs baseline: 1.0075x; 1.0075x over previous
.LBB0_137:
	ds_read_b128 v[128:131], v172
	ds_read_b128 v[152:155], v172 offset:1024
	ds_read_b128 v[156:159], v172 offset:2048
	ds_read_b128 v[160:163], v172 offset:3072
	ds_read_b128 v[182:185], v173
	ds_read_b128 v[188:191], v173 offset:1024
	ds_read_b128 v[192:195], v173 offset:2048
	ds_read_b128 v[204:207], v173 offset:3072
	ds_read_b128 v[208:211], v174
	ds_read_b128 v[212:215], v174 offset:1024
	ds_read_b128 v[216:219], v174 offset:2048
	ds_read_b128 v[222:225], v174 offset:3072
	ds_read_b128 v[226:229], v174 offset:4096
	ds_read_b128 v[230:233], v174 offset:5120
	ds_read_b128 v[234:237], v174 offset:6144
	ds_read_b128 v[238:241], v174 offset:7168
	s_add_u32 s10, s4, 0xfff80080
	s_addc_u32 s11, s5, -1
	s_cmp_eq_u32 s78, 28
	s_cselect_b32 s67, s7, s11
	s_cselect_b32 s66, s9, s10
	s_cselect_b32 s11, s36, s77
	s_cselect_b32 s10, s73, s76
	v_lshl_add_u64 v[196:197], s[4:5], 0, v[144:145]
	s_add_i32 m0, s86, 0xc000
	s_nop 0
	global_load_lds_dwordx4 v[196:197], off
	v_lshl_add_u64 v[196:197], s[4:5], 0, v[146:147]
	s_add_i32 m0, s86, 0xe000
	s_nop 0
	global_load_lds_dwordx4 v[196:197], off
	s_waitcnt vmcnt(8)
	s_waitcnt lgkmcnt(0)
	s_barrier
	s_setprio 1
	s_waitcnt lgkmcnt(0)
	v_mfma_f32_16x16x32_bf16 v[124:127], v[128:131], v[208:211], v[124:127]
	v_mfma_f32_16x16x32_bf16 v[120:123], v[156:159], v[208:211], v[120:123]
	v_mfma_f32_16x16x32_bf16 v[108:111], v[128:131], v[216:219], v[108:111]
	v_mfma_f32_16x16x32_bf16 v[104:107], v[156:159], v[216:219], v[104:107]
	v_mfma_f32_16x16x32_bf16 v[92:95], v[128:131], v[226:229], v[92:95]
	v_mfma_f32_16x16x32_bf16 v[88:91], v[156:159], v[226:229], v[88:91]
	v_mfma_f32_16x16x32_bf16 v[76:79], v[128:131], v[234:237], v[76:79]
	v_mfma_f32_16x16x32_bf16 v[72:75], v[156:159], v[234:237], v[72:75]
	v_mfma_f32_16x16x32_bf16 v[124:127], v[152:155], v[212:215], v[124:127]
	v_mfma_f32_16x16x32_bf16 v[120:123], v[160:163], v[212:215], v[120:123]
	v_mfma_f32_16x16x32_bf16 v[108:111], v[152:155], v[222:225], v[108:111]
	v_mfma_f32_16x16x32_bf16 v[104:107], v[160:163], v[222:225], v[104:107]
	v_mfma_f32_16x16x32_bf16 v[92:95], v[152:155], v[230:233], v[92:95]
	v_mfma_f32_16x16x32_bf16 v[88:91], v[160:163], v[230:233], v[88:91]
	v_mfma_f32_16x16x32_bf16 v[76:79], v[152:155], v[238:241], v[76:79]
	v_mfma_f32_16x16x32_bf16 v[72:75], v[160:163], v[238:241], v[72:75]
	s_setprio 0
	s_setprio 1
	v_mfma_f32_16x16x32_bf16 v[116:119], v[182:185], v[208:211], v[116:119]
	v_mfma_f32_16x16x32_bf16 v[112:115], v[192:195], v[208:211], v[112:115]
	v_mfma_f32_16x16x32_bf16 v[100:103], v[182:185], v[216:219], v[100:103]
	v_mfma_f32_16x16x32_bf16 v[96:99], v[192:195], v[216:219], v[96:99]
	v_mfma_f32_16x16x32_bf16 v[84:87], v[182:185], v[226:229], v[84:87]
	v_mfma_f32_16x16x32_bf16 v[80:83], v[192:195], v[226:229], v[80:83]
	v_mfma_f32_16x16x32_bf16 v[68:71], v[182:185], v[234:237], v[68:71]
	v_mfma_f32_16x16x32_bf16 v[64:67], v[192:195], v[234:237], v[64:67]
	v_mfma_f32_16x16x32_bf16 v[116:119], v[188:191], v[212:215], v[116:119]
	v_mfma_f32_16x16x32_bf16 v[112:115], v[204:207], v[212:215], v[112:115]
	v_mfma_f32_16x16x32_bf16 v[100:103], v[188:191], v[222:225], v[100:103]
	v_mfma_f32_16x16x32_bf16 v[96:99], v[204:207], v[222:225], v[96:99]
	v_mfma_f32_16x16x32_bf16 v[84:87], v[188:191], v[230:233], v[84:87]
	v_mfma_f32_16x16x32_bf16 v[80:83], v[204:207], v[230:233], v[80:83]
	v_mfma_f32_16x16x32_bf16 v[68:71], v[188:191], v[238:241], v[68:71]
	v_mfma_f32_16x16x32_bf16 v[64:67], v[204:207], v[238:241], v[64:67]
	s_setprio 0
	s_barrier
	ds_read_b128 v[208:211], v174 offset:16384
	ds_read_b128 v[212:215], v174 offset:17408
	ds_read_b128 v[216:219], v174 offset:18432
	ds_read_b128 v[222:225], v174 offset:19456
	ds_read_b128 v[226:229], v174 offset:20480
	ds_read_b128 v[230:233], v174 offset:21504
	ds_read_b128 v[234:237], v174 offset:22528
	ds_read_b128 v[238:241], v174 offset:23552
	s_add_i32 s34, s53, s81
	v_lshl_add_u64 v[196:197], s[10:11], 0, v[134:135]
	s_mov_b32 m0, s34
	s_nop 0
	global_load_lds_dwordx4 v[196:197], off
	s_add_i32 m0, s34, 0x2000
	s_add_u32 s34, s10, 0x80000
	v_lshl_add_u64 v[242:243], s[10:11], 0, v[138:139]
	s_addc_u32 s35, s11, 0
	s_add_i32 s79, s19, s81
	global_load_lds_dwordx4 v[242:243], off
	v_lshl_add_u64 v[244:245], s[34:35], 0, v[134:135]
	s_mov_b32 m0, s79
	v_lshl_add_u64 v[246:247], s[66:67], 0, v[136:137]
	global_load_lds_dwordx4 v[244:245], off
	v_lshl_add_u64 v[244:245], s[34:35], 0, v[138:139]
	s_add_i32 m0, s79, 0x2000
	s_nop 0
	global_load_lds_dwordx4 v[244:245], off
	v_lshl_add_u64 v[244:245], s[66:67], 0, v[132:133]
	s_mov_b32 m0, s86
	s_nop 0
	global_load_lds_dwordx4 v[244:245], off
	s_mov_b32 m0, s87
	s_nop 0
	global_load_lds_dwordx4 v[246:247], off
	s_waitcnt vmcnt(8)
	s_waitcnt lgkmcnt(0)
	s_barrier
	s_setprio 1
	s_waitcnt lgkmcnt(0)
	v_mfma_f32_16x16x32_bf16 v[60:63], v[128:131], v[208:211], v[60:63]
	v_mfma_f32_16x16x32_bf16 v[56:59], v[156:159], v[208:211], v[56:59]
	v_mfma_f32_16x16x32_bf16 v[44:47], v[128:131], v[216:219], v[44:47]
	v_mfma_f32_16x16x32_bf16 v[40:43], v[156:159], v[216:219], v[40:43]
	v_mfma_f32_16x16x32_bf16 v[28:31], v[128:131], v[226:229], v[28:31]
	v_mfma_f32_16x16x32_bf16 v[24:27], v[156:159], v[226:229], v[24:27]
	v_mfma_f32_16x16x32_bf16 v[12:15], v[128:131], v[234:237], v[12:15]
	v_mfma_f32_16x16x32_bf16 v[8:11], v[156:159], v[234:237], v[8:11]
	v_mfma_f32_16x16x32_bf16 v[60:63], v[152:155], v[212:215], v[60:63]
	v_mfma_f32_16x16x32_bf16 v[56:59], v[160:163], v[212:215], v[56:59]
	v_mfma_f32_16x16x32_bf16 v[44:47], v[152:155], v[222:225], v[44:47]
	v_mfma_f32_16x16x32_bf16 v[40:43], v[160:163], v[222:225], v[40:43]
	v_mfma_f32_16x16x32_bf16 v[28:31], v[152:155], v[230:233], v[28:31]
	v_mfma_f32_16x16x32_bf16 v[24:27], v[160:163], v[230:233], v[24:27]
	v_mfma_f32_16x16x32_bf16 v[12:15], v[152:155], v[238:241], v[12:15]
	v_mfma_f32_16x16x32_bf16 v[8:11], v[160:163], v[238:241], v[8:11]
	s_setprio 0
	s_setprio 1
	v_mfma_f32_16x16x32_bf16 v[52:55], v[182:185], v[208:211], v[52:55]
	v_mfma_f32_16x16x32_bf16 v[48:51], v[192:195], v[208:211], v[48:51]
	v_mfma_f32_16x16x32_bf16 v[36:39], v[182:185], v[216:219], v[36:39]
	v_mfma_f32_16x16x32_bf16 v[32:35], v[192:195], v[216:219], v[32:35]
	v_mfma_f32_16x16x32_bf16 v[20:23], v[182:185], v[226:229], v[20:23]
	v_mfma_f32_16x16x32_bf16 v[16:19], v[192:195], v[226:229], v[16:19]
	v_mfma_f32_16x16x32_bf16 v[4:7], v[182:185], v[234:237], v[4:7]
	v_mfma_f32_16x16x32_bf16 v[0:3], v[192:195], v[234:237], v[0:3]
	v_mfma_f32_16x16x32_bf16 v[52:55], v[188:191], v[212:215], v[52:55]
	v_mfma_f32_16x16x32_bf16 v[48:51], v[204:207], v[212:215], v[48:51]
	v_mfma_f32_16x16x32_bf16 v[36:39], v[188:191], v[222:225], v[36:39]
	v_mfma_f32_16x16x32_bf16 v[32:35], v[204:207], v[222:225], v[32:35]
	v_mfma_f32_16x16x32_bf16 v[20:23], v[188:191], v[230:233], v[20:23]
	v_mfma_f32_16x16x32_bf16 v[16:19], v[204:207], v[230:233], v[16:19]
	v_mfma_f32_16x16x32_bf16 v[4:7], v[188:191], v[238:241], v[4:7]
	v_mfma_f32_16x16x32_bf16 v[0:3], v[204:207], v[238:241], v[0:3]
	s_setprio 0
	s_barrier
	s_add_i32 s79, 0, 0x18000
	v_add_u32_e32 v140, s79, v164
	s_add_i32 s84, 0, 0x1c000
	ds_read_b128 v[128:131], v140
	ds_read_b128 v[152:155], v140 offset:1024
	ds_read_b128 v[156:159], v140 offset:2048
	ds_read_b128 v[160:163], v140 offset:3072
	v_add_u32_e32 v140, s84, v164
	ds_read_b128 v[182:185], v140
	ds_read_b128 v[188:191], v140 offset:1024
	ds_read_b128 v[192:195], v140 offset:2048
	ds_read_b128 v[204:207], v140 offset:3072
	ds_read_b128 v[208:211], v174 offset:32768
	ds_read_b128 v[212:215], v174 offset:33792
	ds_read_b128 v[216:219], v174 offset:34816
	ds_read_b128 v[222:225], v174 offset:35840
	ds_read_b128 v[226:229], v174 offset:36864
	ds_read_b128 v[230:233], v174 offset:37888
	ds_read_b128 v[234:237], v174 offset:38912
	ds_read_b128 v[238:241], v174 offset:39936
	s_add_u32 s34, s66, 0x80000
	s_addc_u32 s35, s67, 0
	s_mov_b32 m0, s88
	v_lshl_add_u64 v[248:249], s[34:35], 0, v[132:133]
	global_load_lds_dwordx4 v[248:249], off
	v_lshl_add_u64 v[248:249], s[34:35], 0, v[136:137]
	s_mov_b32 m0, s89
	s_nop 0
	global_load_lds_dwordx4 v[248:249], off
	s_waitcnt vmcnt(8)
	s_waitcnt lgkmcnt(0)
	s_barrier
	s_setprio 1
	s_waitcnt lgkmcnt(0)
	v_mfma_f32_16x16x32_bf16 v[124:127], v[128:131], v[208:211], v[124:127]
	v_mfma_f32_16x16x32_bf16 v[120:123], v[156:159], v[208:211], v[120:123]
	v_mfma_f32_16x16x32_bf16 v[108:111], v[128:131], v[216:219], v[108:111]
	v_mfma_f32_16x16x32_bf16 v[104:107], v[156:159], v[216:219], v[104:107]
	v_mfma_f32_16x16x32_bf16 v[92:95], v[128:131], v[226:229], v[92:95]
	v_mfma_f32_16x16x32_bf16 v[88:91], v[156:159], v[226:229], v[88:91]
	v_mfma_f32_16x16x32_bf16 v[76:79], v[128:131], v[234:237], v[76:79]
	v_mfma_f32_16x16x32_bf16 v[72:75], v[156:159], v[234:237], v[72:75]
	v_mfma_f32_16x16x32_bf16 v[124:127], v[152:155], v[212:215], v[124:127]
	v_mfma_f32_16x16x32_bf16 v[120:123], v[160:163], v[212:215], v[120:123]
	v_mfma_f32_16x16x32_bf16 v[108:111], v[152:155], v[222:225], v[108:111]
	v_mfma_f32_16x16x32_bf16 v[104:107], v[160:163], v[222:225], v[104:107]
	v_mfma_f32_16x16x32_bf16 v[92:95], v[152:155], v[230:233], v[92:95]
	v_mfma_f32_16x16x32_bf16 v[88:91], v[160:163], v[230:233], v[88:91]
	v_mfma_f32_16x16x32_bf16 v[76:79], v[152:155], v[238:241], v[76:79]
	v_mfma_f32_16x16x32_bf16 v[72:75], v[160:163], v[238:241], v[72:75]
	s_setprio 0
	s_setprio 1
	v_mfma_f32_16x16x32_bf16 v[116:119], v[182:185], v[208:211], v[116:119]
	v_mfma_f32_16x16x32_bf16 v[112:115], v[192:195], v[208:211], v[112:115]
	v_mfma_f32_16x16x32_bf16 v[100:103], v[182:185], v[216:219], v[100:103]
	v_mfma_f32_16x16x32_bf16 v[96:99], v[192:195], v[216:219], v[96:99]
	v_mfma_f32_16x16x32_bf16 v[84:87], v[182:185], v[226:229], v[84:87]
	v_mfma_f32_16x16x32_bf16 v[80:83], v[192:195], v[226:229], v[80:83]
	v_mfma_f32_16x16x32_bf16 v[68:71], v[182:185], v[234:237], v[68:71]
	v_mfma_f32_16x16x32_bf16 v[64:67], v[192:195], v[234:237], v[64:67]
	v_mfma_f32_16x16x32_bf16 v[116:119], v[188:191], v[212:215], v[116:119]
	v_mfma_f32_16x16x32_bf16 v[112:115], v[204:207], v[212:215], v[112:115]
	v_mfma_f32_16x16x32_bf16 v[100:103], v[188:191], v[222:225], v[100:103]
	v_mfma_f32_16x16x32_bf16 v[96:99], v[204:207], v[222:225], v[96:99]
	v_mfma_f32_16x16x32_bf16 v[84:87], v[188:191], v[230:233], v[84:87]
	v_mfma_f32_16x16x32_bf16 v[80:83], v[204:207], v[230:233], v[80:83]
	v_mfma_f32_16x16x32_bf16 v[68:71], v[188:191], v[238:241], v[68:71]
	v_mfma_f32_16x16x32_bf16 v[64:67], v[204:207], v[238:241], v[64:67]
	s_setprio 0
	s_barrier
; #define PG8_BAR __builtin_amdgcn_s_barrier()
; template <class Epi>
; __device__ __forceinline__ void gemm_phase(LAS unsigned char* lds, const Gemm g, const StaticOrder& S, const Epi& E) {
;     ...
;         if (wr == 0) PG8_BAR;
	ds_read_b128 v[208:211], v174 offset:49152
	ds_read_b128 v[212:215], v174 offset:50176
	ds_read_b128 v[216:219], v174 offset:51200
	ds_read_b128 v[222:225], v174 offset:52224
	ds_read_b128 v[226:229], v174 offset:53248
	ds_read_b128 v[230:233], v174 offset:54272
	ds_read_b128 v[234:237], v174 offset:55296
	ds_read_b128 v[238:241], v174 offset:56320
	s_add_i32 s34, s79, s81
	v_lshl_add_u64 v[196:197], v[196:197], 0, s[50:51]
	s_mov_b32 m0, s34
	s_nop 0
	global_load_lds_dwordx4 v[196:197], off
	s_add_i32 m0, s34, 0x2000
	s_add_u32 s10, s10, 0x80080
	v_lshl_add_u64 v[196:197], v[242:243], 0, s[50:51]
	s_addc_u32 s11, s11, 0
	s_add_i32 s34, s84, s81
	global_load_lds_dwordx4 v[196:197], off
	v_lshl_add_u64 v[196:197], s[10:11], 0, v[134:135]
	s_mov_b32 m0, s34
	s_nop 0
	global_load_lds_dwordx4 v[196:197], off
	v_lshl_add_u64 v[196:197], s[10:11], 0, v[138:139]
	s_add_i32 m0, s34, 0x2000
	s_nop 0
	global_load_lds_dwordx4 v[196:197], off
	v_lshl_add_u64 v[196:197], v[244:245], 0, s[50:51]
	s_mov_b32 m0, s40
	s_nop 0
	global_load_lds_dwordx4 v[196:197], off
	v_lshl_add_u64 v[196:197], v[246:247], 0, s[50:51]
	s_mov_b32 m0, s41
	s_nop 0
	global_load_lds_dwordx4 v[196:197], off
	s_waitcnt vmcnt(8)
	s_waitcnt lgkmcnt(0)
	s_barrier
	s_setprio 1
	s_waitcnt lgkmcnt(0)
	v_mfma_f32_16x16x32_bf16 v[60:63], v[128:131], v[208:211], v[60:63]
	v_mfma_f32_16x16x32_bf16 v[56:59], v[156:159], v[208:211], v[56:59]
	v_mfma_f32_16x16x32_bf16 v[44:47], v[128:131], v[216:219], v[44:47]
	v_mfma_f32_16x16x32_bf16 v[40:43], v[156:159], v[216:219], v[40:43]
	v_mfma_f32_16x16x32_bf16 v[28:31], v[128:131], v[226:229], v[28:31]
	v_mfma_f32_16x16x32_bf16 v[24:27], v[156:159], v[226:229], v[24:27]
	v_mfma_f32_16x16x32_bf16 v[12:15], v[128:131], v[234:237], v[12:15]
	v_mfma_f32_16x16x32_bf16 v[8:11], v[156:159], v[234:237], v[8:11]
	v_mfma_f32_16x16x32_bf16 v[60:63], v[152:155], v[212:215], v[60:63]
	v_mfma_f32_16x16x32_bf16 v[56:59], v[160:163], v[212:215], v[56:59]
	v_mfma_f32_16x16x32_bf16 v[44:47], v[152:155], v[222:225], v[44:47]
	v_mfma_f32_16x16x32_bf16 v[40:43], v[160:163], v[222:225], v[40:43]
	v_mfma_f32_16x16x32_bf16 v[28:31], v[152:155], v[230:233], v[28:31]
	v_mfma_f32_16x16x32_bf16 v[24:27], v[160:163], v[230:233], v[24:27]
	v_mfma_f32_16x16x32_bf16 v[12:15], v[152:155], v[238:241], v[12:15]
	v_mfma_f32_16x16x32_bf16 v[8:11], v[160:163], v[238:241], v[8:11]
	s_setprio 0
	s_setprio 1
	v_mfma_f32_16x16x32_bf16 v[52:55], v[182:185], v[208:211], v[52:55]
	v_mfma_f32_16x16x32_bf16 v[48:51], v[192:195], v[208:211], v[48:51]
	v_mfma_f32_16x16x32_bf16 v[36:39], v[182:185], v[216:219], v[36:39]
	v_mfma_f32_16x16x32_bf16 v[32:35], v[192:195], v[216:219], v[32:35]
	v_mfma_f32_16x16x32_bf16 v[20:23], v[182:185], v[226:229], v[20:23]
	v_mfma_f32_16x16x32_bf16 v[16:19], v[192:195], v[226:229], v[16:19]
	v_mfma_f32_16x16x32_bf16 v[4:7], v[182:185], v[234:237], v[4:7]
	v_mfma_f32_16x16x32_bf16 v[0:3], v[192:195], v[234:237], v[0:3]
	v_mfma_f32_16x16x32_bf16 v[52:55], v[188:191], v[212:215], v[52:55]
	v_mfma_f32_16x16x32_bf16 v[48:51], v[204:207], v[212:215], v[48:51]
	v_mfma_f32_16x16x32_bf16 v[36:39], v[188:191], v[222:225], v[36:39]
	v_mfma_f32_16x16x32_bf16 v[32:35], v[204:207], v[222:225], v[32:35]
	v_mfma_f32_16x16x32_bf16 v[20:23], v[188:191], v[230:233], v[20:23]
	v_mfma_f32_16x16x32_bf16 v[16:19], v[204:207], v[230:233], v[16:19]
	v_mfma_f32_16x16x32_bf16 v[4:7], v[188:191], v[238:241], v[4:7]
	v_mfma_f32_16x16x32_bf16 v[0:3], v[204:207], v[238:241], v[0:3]
	s_setprio 0
	s_barrier
	s_add_i32 s78, s78, 2
	s_add_u32 s4, s4, 0x100
	s_addc_u32 s5, s5, 0
	s_add_u32 s76, s76, 0x100
	s_addc_u32 s77, s77, 0
	s_cmp_gt_u32 s78, 29
	s_cbranch_scc0 .LBB0_137
	v_readlane_b32 s4, v250, 24
	v_readlane_b32 s5, v250, 25
	s_and_b64 vcc, exec, s[4:5]
	s_cbranch_vccz .LBB0_140
	s_barrier

.LBB0_701:
	ds_read_b128 v[148:151], v144
	ds_read_b128 v[152:155], v144 offset:1024
	ds_read_b128 v[156:159], v144 offset:2048
	ds_read_b128 v[160:163], v144 offset:3072
	ds_read_b128 v[164:167], v145
	ds_read_b128 v[168:171], v145 offset:1024
	ds_read_b128 v[172:175], v145 offset:2048
	ds_read_b128 v[180:183], v145 offset:3072
	ds_read_b128 v[184:187], v146
	ds_read_b128 v[188:191], v146 offset:1024
	ds_read_b128 v[192:195], v146 offset:2048
	ds_read_b128 v[196:199], v146 offset:3072
	ds_read_b128 v[200:203], v146 offset:4096
	ds_read_b128 v[204:207], v146 offset:5120
	ds_read_b128 v[208:211], v146 offset:6144
	ds_read_b128 v[212:215], v146 offset:7168
	s_add_u32 s34, s0, 0xfff80080
	s_addc_u32 s35, s1, -1
	s_cmp_eq_u32 s57, 12
	s_cselect_b32 s55, s79, s35
	s_cselect_b32 s54, s11, s34
	s_cselect_b32 s49, s63, s56
	s_cselect_b32 s48, s62, s9
	s_mov_b32 m0, s66
	v_lshl_add_u64 v[138:139], s[0:1], 0, v[128:129]
	global_load_lds_dwordx4 v[138:139], off
	v_lshl_add_u64 v[138:139], s[0:1], 0, v[132:133]
	s_mov_b32 m0, s67
	s_nop 0
	global_load_lds_dwordx4 v[138:139], off
	s_waitcnt vmcnt(8)
	s_waitcnt lgkmcnt(0)
	s_barrier
	s_setprio 1
	s_waitcnt lgkmcnt(0)
	v_mfma_f32_16x16x32_bf16 v[8:11], v[148:151], v[184:187], v[8:11]
	v_mfma_f32_16x16x32_bf16 v[12:15], v[156:159], v[184:187], v[12:15]
	v_mfma_f32_16x16x32_bf16 v[40:43], v[148:151], v[192:195], v[40:43]
	v_mfma_f32_16x16x32_bf16 v[44:47], v[156:159], v[192:195], v[44:47]
	v_mfma_f32_16x16x32_bf16 v[64:67], v[148:151], v[200:203], v[64:67]
	v_mfma_f32_16x16x32_bf16 v[68:71], v[156:159], v[200:203], v[68:71]
	v_mfma_f32_16x16x32_bf16 v[88:91], v[148:151], v[208:211], v[88:91]
	v_mfma_f32_16x16x32_bf16 v[92:95], v[156:159], v[208:211], v[92:95]
	v_mfma_f32_16x16x32_bf16 v[8:11], v[152:155], v[188:191], v[8:11]
	v_mfma_f32_16x16x32_bf16 v[12:15], v[160:163], v[188:191], v[12:15]
	v_mfma_f32_16x16x32_bf16 v[40:43], v[152:155], v[196:199], v[40:43]
	v_mfma_f32_16x16x32_bf16 v[44:47], v[160:163], v[196:199], v[44:47]
	v_mfma_f32_16x16x32_bf16 v[64:67], v[152:155], v[204:207], v[64:67]
	v_mfma_f32_16x16x32_bf16 v[68:71], v[160:163], v[204:207], v[68:71]
	v_mfma_f32_16x16x32_bf16 v[88:91], v[152:155], v[212:215], v[88:91]
	v_mfma_f32_16x16x32_bf16 v[92:95], v[160:163], v[212:215], v[92:95]
	s_setprio 0
	s_setprio 1
	v_mfma_f32_16x16x32_bf16 v[28:31], v[164:167], v[184:187], v[28:31]
	v_mfma_f32_16x16x32_bf16 v[24:27], v[172:175], v[184:187], v[24:27]
	v_mfma_f32_16x16x32_bf16 v[48:51], v[164:167], v[192:195], v[48:51]
	v_mfma_f32_16x16x32_bf16 v[52:55], v[172:175], v[192:195], v[52:55]
	v_mfma_f32_16x16x32_bf16 v[72:75], v[164:167], v[200:203], v[72:75]
	v_mfma_f32_16x16x32_bf16 v[76:79], v[172:175], v[200:203], v[76:79]
	v_mfma_f32_16x16x32_bf16 v[96:99], v[164:167], v[208:211], v[96:99]
	v_mfma_f32_16x16x32_bf16 v[100:103], v[172:175], v[208:211], v[100:103]
	v_mfma_f32_16x16x32_bf16 v[28:31], v[168:171], v[188:191], v[28:31]
	v_mfma_f32_16x16x32_bf16 v[24:27], v[180:183], v[188:191], v[24:27]
	v_mfma_f32_16x16x32_bf16 v[48:51], v[168:171], v[196:199], v[48:51]
	v_mfma_f32_16x16x32_bf16 v[52:55], v[180:183], v[196:199], v[52:55]
	v_mfma_f32_16x16x32_bf16 v[72:75], v[168:171], v[204:207], v[72:75]
	v_mfma_f32_16x16x32_bf16 v[76:79], v[180:183], v[204:207], v[76:79]
	v_mfma_f32_16x16x32_bf16 v[96:99], v[168:171], v[212:215], v[96:99]
	v_mfma_f32_16x16x32_bf16 v[100:103], v[180:183], v[212:215], v[100:103]
	s_setprio 0
	s_barrier
	ds_read_b128 v[184:187], v146 offset:16384
	ds_read_b128 v[188:191], v146 offset:17408
	ds_read_b128 v[192:195], v146 offset:18432
	ds_read_b128 v[196:199], v146 offset:19456
	ds_read_b128 v[200:203], v146 offset:20480
	ds_read_b128 v[204:207], v146 offset:21504
	ds_read_b128 v[208:211], v146 offset:22528
	ds_read_b128 v[212:215], v146 offset:23552
	s_mov_b32 m0, s72
	v_lshl_add_u64 v[216:217], s[48:49], 0, v[130:131]
	s_add_u32 s34, s48, 0x80000
	global_load_lds_dwordx4 v[216:217], off
	v_lshl_add_u64 v[218:219], s[48:49], 0, v[134:135]
	s_mov_b32 m0, s73
	s_addc_u32 s35, s49, 0
	global_load_lds_dwordx4 v[218:219], off
	v_lshl_add_u64 v[138:139], s[34:35], 0, v[130:131]
	s_mov_b32 m0, s74
	v_lshl_add_u64 v[222:223], s[54:55], 0, v[128:129]
	global_load_lds_dwordx4 v[138:139], off
	v_lshl_add_u64 v[138:139], s[34:35], 0, v[134:135]
	s_mov_b32 m0, s76
	v_lshl_add_u64 v[224:225], s[54:55], 0, v[132:133]
	global_load_lds_dwordx4 v[138:139], off
	s_mov_b32 m0, s36
	s_nop 0
	global_load_lds_dwordx4 v[222:223], off
	s_mov_b32 m0, s37
	s_nop 0
	global_load_lds_dwordx4 v[224:225], off
	s_waitcnt vmcnt(8)
	s_waitcnt lgkmcnt(0)
	s_barrier
	s_setprio 1
	s_waitcnt lgkmcnt(0)
	v_mfma_f32_16x16x32_bf16 v[112:115], v[148:151], v[184:187], v[112:115]
	v_mfma_f32_16x16x32_bf16 v[116:119], v[156:159], v[184:187], v[116:119]
	v_mfma_f32_16x16x32_bf16 v[108:111], v[148:151], v[192:195], v[108:111]
	v_mfma_f32_16x16x32_bf16 v[104:107], v[156:159], v[192:195], v[104:107]
	v_mfma_f32_16x16x32_bf16 v[60:63], v[148:151], v[200:203], v[60:63]
	v_mfma_f32_16x16x32_bf16 v[56:59], v[156:159], v[200:203], v[56:59]
	v_mfma_f32_16x16x32_bf16 v[20:23], v[148:151], v[208:211], v[20:23]
	v_mfma_f32_16x16x32_bf16 v[16:19], v[156:159], v[208:211], v[16:19]
	v_mfma_f32_16x16x32_bf16 v[112:115], v[152:155], v[188:191], v[112:115]
	v_mfma_f32_16x16x32_bf16 v[116:119], v[160:163], v[188:191], v[116:119]
	v_mfma_f32_16x16x32_bf16 v[108:111], v[152:155], v[196:199], v[108:111]
	v_mfma_f32_16x16x32_bf16 v[104:107], v[160:163], v[196:199], v[104:107]
	v_mfma_f32_16x16x32_bf16 v[60:63], v[152:155], v[204:207], v[60:63]
	v_mfma_f32_16x16x32_bf16 v[56:59], v[160:163], v[204:207], v[56:59]
	v_mfma_f32_16x16x32_bf16 v[20:23], v[152:155], v[212:215], v[20:23]
	v_mfma_f32_16x16x32_bf16 v[16:19], v[160:163], v[212:215], v[16:19]
	s_setprio 0
	s_setprio 1
	v_mfma_f32_16x16x32_bf16 v[124:127], v[164:167], v[184:187], v[124:127]
	v_mfma_f32_16x16x32_bf16 v[120:123], v[172:175], v[184:187], v[120:123]
	v_mfma_f32_16x16x32_bf16 v[84:87], v[164:167], v[192:195], v[84:87]
	v_mfma_f32_16x16x32_bf16 v[80:83], v[172:175], v[192:195], v[80:83]
	v_mfma_f32_16x16x32_bf16 v[36:39], v[164:167], v[200:203], v[36:39]
	v_mfma_f32_16x16x32_bf16 v[32:35], v[172:175], v[200:203], v[32:35]
	v_mfma_f32_16x16x32_bf16 v[4:7], v[164:167], v[208:211], v[4:7]
	v_mfma_f32_16x16x32_bf16 v[0:3], v[172:175], v[208:211], v[0:3]
	v_mfma_f32_16x16x32_bf16 v[124:127], v[168:171], v[188:191], v[124:127]
	v_mfma_f32_16x16x32_bf16 v[120:123], v[180:183], v[188:191], v[120:123]
	v_mfma_f32_16x16x32_bf16 v[84:87], v[168:171], v[196:199], v[84:87]
	v_mfma_f32_16x16x32_bf16 v[80:83], v[180:183], v[196:199], v[80:83]
	v_mfma_f32_16x16x32_bf16 v[36:39], v[168:171], v[204:207], v[36:39]
	v_mfma_f32_16x16x32_bf16 v[32:35], v[180:183], v[204:207], v[32:35]
	v_mfma_f32_16x16x32_bf16 v[4:7], v[168:171], v[212:215], v[4:7]
	v_mfma_f32_16x16x32_bf16 v[0:3], v[180:183], v[212:215], v[0:3]
	s_setprio 0
	s_barrier
	s_add_i32 s82, 0, 0x1c000
	v_add_u32_e32 v138, s82, v140
	ds_read_b128 v[148:151], v147
	ds_read_b128 v[152:155], v147 offset:1024
	ds_read_b128 v[156:159], v147 offset:2048
	ds_read_b128 v[160:163], v147 offset:3072
	ds_read_b128 v[164:167], v138
	ds_read_b128 v[168:171], v138 offset:1024
	ds_read_b128 v[172:175], v138 offset:2048
	ds_read_b128 v[180:183], v138 offset:3072
	ds_read_b128 v[184:187], v146 offset:32768
	ds_read_b128 v[188:191], v146 offset:33792
	ds_read_b128 v[192:195], v146 offset:34816
	ds_read_b128 v[196:199], v146 offset:35840
	ds_read_b128 v[200:203], v146 offset:36864
	ds_read_b128 v[204:207], v146 offset:37888
	ds_read_b128 v[208:211], v146 offset:38912
	ds_read_b128 v[212:215], v146 offset:39936
	s_add_u32 s34, s54, 0x80000
	s_addc_u32 s35, s55, 0
	s_mov_b32 m0, s40
	v_lshl_add_u64 v[226:227], s[34:35], 0, v[128:129]
	global_load_lds_dwordx4 v[226:227], off
	v_lshl_add_u64 v[226:227], s[34:35], 0, v[132:133]
	s_mov_b32 m0, s41
	s_nop 0
	global_load_lds_dwordx4 v[226:227], off
	s_waitcnt vmcnt(8)
	s_waitcnt lgkmcnt(0)
	s_barrier
	s_setprio 1
	s_waitcnt lgkmcnt(0)
	v_mfma_f32_16x16x32_bf16 v[8:11], v[148:151], v[184:187], v[8:11]
	v_mfma_f32_16x16x32_bf16 v[12:15], v[156:159], v[184:187], v[12:15]
	v_mfma_f32_16x16x32_bf16 v[40:43], v[148:151], v[192:195], v[40:43]
	v_mfma_f32_16x16x32_bf16 v[44:47], v[156:159], v[192:195], v[44:47]
	v_mfma_f32_16x16x32_bf16 v[64:67], v[148:151], v[200:203], v[64:67]
	v_mfma_f32_16x16x32_bf16 v[68:71], v[156:159], v[200:203], v[68:71]
	v_mfma_f32_16x16x32_bf16 v[88:91], v[148:151], v[208:211], v[88:91]
	v_mfma_f32_16x16x32_bf16 v[92:95], v[156:159], v[208:211], v[92:95]
	v_mfma_f32_16x16x32_bf16 v[8:11], v[152:155], v[188:191], v[8:11]
	v_mfma_f32_16x16x32_bf16 v[12:15], v[160:163], v[188:191], v[12:15]
	v_mfma_f32_16x16x32_bf16 v[40:43], v[152:155], v[196:199], v[40:43]
	v_mfma_f32_16x16x32_bf16 v[44:47], v[160:163], v[196:199], v[44:47]
	v_mfma_f32_16x16x32_bf16 v[64:67], v[152:155], v[204:207], v[64:67]
	v_mfma_f32_16x16x32_bf16 v[68:71], v[160:163], v[204:207], v[68:71]
	v_mfma_f32_16x16x32_bf16 v[88:91], v[152:155], v[212:215], v[88:91]
	v_mfma_f32_16x16x32_bf16 v[92:95], v[160:163], v[212:215], v[92:95]
	s_setprio 0
	s_setprio 1
	v_mfma_f32_16x16x32_bf16 v[28:31], v[164:167], v[184:187], v[28:31]
	v_mfma_f32_16x16x32_bf16 v[24:27], v[172:175], v[184:187], v[24:27]
	v_mfma_f32_16x16x32_bf16 v[48:51], v[164:167], v[192:195], v[48:51]
	v_mfma_f32_16x16x32_bf16 v[52:55], v[172:175], v[192:195], v[52:55]
	v_mfma_f32_16x16x32_bf16 v[72:75], v[164:167], v[200:203], v[72:75]
	v_mfma_f32_16x16x32_bf16 v[76:79], v[172:175], v[200:203], v[76:79]
	v_mfma_f32_16x16x32_bf16 v[96:99], v[164:167], v[208:211], v[96:99]
	v_mfma_f32_16x16x32_bf16 v[100:103], v[172:175], v[208:211], v[100:103]
	v_mfma_f32_16x16x32_bf16 v[28:31], v[168:171], v[188:191], v[28:31]
	v_mfma_f32_16x16x32_bf16 v[24:27], v[180:183], v[188:191], v[24:27]
	v_mfma_f32_16x16x32_bf16 v[48:51], v[168:171], v[196:199], v[48:51]
	v_mfma_f32_16x16x32_bf16 v[52:55], v[180:183], v[196:199], v[52:55]
	v_mfma_f32_16x16x32_bf16 v[72:75], v[168:171], v[204:207], v[72:75]
	v_mfma_f32_16x16x32_bf16 v[76:79], v[180:183], v[204:207], v[76:79]
	v_mfma_f32_16x16x32_bf16 v[96:99], v[168:171], v[212:215], v[96:99]
	v_mfma_f32_16x16x32_bf16 v[100:103], v[180:183], v[212:215], v[100:103]
	s_setprio 0
	s_barrier
;         unsigned lo_ = (unsigned)((wr * 64 + fr) * PLD + wc * 32 + 8 * fq) * 2u; asm volatile("" : "+v"(lo_));
;         const char* pb = (const char*)proj + (((size_t)u.pm * 256 + u.ra) * PLD + u.pn * 256 + u.cb) * 2;
; #pragma unroll
;         for (int ai = 0; ai < NAI; ++ai)
; #pragma unroll
;             for (int m = 0; m < 4; ++m) {
; #pragma unroll
;                 for (int bj = 0; bj < NBJ; ++bj) {
;                     const unsigned off = lo_ + (unsigned)(((ai * 128 + m * 16) * PLD + bj * 128) * 2);
;                     const u32x4 rv = *(const u32x4*)(pb + off + PC_GA * 2);
;                     acc[ai][bj][m][0][0] *= bflo(rv[0]); acc[ai][bj][m][0][1] *= bfhi(rv[0]); acc[ai][bj][m][0][2] *= bflo(rv[1]); acc[ai][bj][m][0][3] *= bfhi(rv[1]);
;                     acc[ai][bj][m][1][0] *= bflo(rv[2]); acc[ai][bj][m][1][1] *= bfhi(rv[2]); acc[ai][bj][m][1][2] *= bflo(rv[3]); acc[ai][bj][m][1][3] *= bfhi(rv[3]);
;                     asm volatile("" : "+v"(acc[ai][bj][m][0]), "+v"(acc[ai][bj][m][1]) :: "memory");
	ds_read_b128 v[184:187], v146 offset:49152
	ds_read_b128 v[188:191], v146 offset:50176
	ds_read_b128 v[192:195], v146 offset:51200
	ds_read_b128 v[196:199], v146 offset:52224
	ds_read_b128 v[200:203], v146 offset:53248
	ds_read_b128 v[204:207], v146 offset:54272
	ds_read_b128 v[208:211], v146 offset:55296
	ds_read_b128 v[212:215], v146 offset:56320
	s_add_i32 s80, s77, s14
	s_add_i32 s81, s80, 0x2000
	v_lshl_add_u64 v[216:217], v[216:217], 0, s[22:23]
	s_mov_b32 m0, s80
	s_add_u32 s34, s48, 0x80080
	global_load_lds_dwordx4 v[216:217], off
	v_lshl_add_u64 v[216:217], v[218:219], 0, s[22:23]
	s_mov_b32 m0, s81
	s_addc_u32 s35, s49, 0
	s_add_i32 s82, s82, s14
	global_load_lds_dwordx4 v[216:217], off
	v_lshl_add_u64 v[216:217], s[34:35], 0, v[130:131]
	s_mov_b32 m0, s82
	s_add_i32 s83, s82, 0x2000
	global_load_lds_dwordx4 v[216:217], off
	v_lshl_add_u64 v[216:217], s[34:35], 0, v[134:135]
	s_mov_b32 m0, s83
	s_nop 0
	global_load_lds_dwordx4 v[216:217], off
	v_lshl_add_u64 v[216:217], v[222:223], 0, s[22:23]
	s_mov_b32 m0, s43
	s_nop 0
	global_load_lds_dwordx4 v[216:217], off
	v_lshl_add_u64 v[216:217], v[224:225], 0, s[22:23]
	s_mov_b32 m0, s64
	s_nop 0
	global_load_lds_dwordx4 v[216:217], off
	s_waitcnt vmcnt(8)
	s_waitcnt lgkmcnt(0)
	s_barrier
	s_setprio 1
	s_waitcnt lgkmcnt(0)
	v_mfma_f32_16x16x32_bf16 v[112:115], v[148:151], v[184:187], v[112:115]
	v_mfma_f32_16x16x32_bf16 v[116:119], v[156:159], v[184:187], v[116:119]
	v_mfma_f32_16x16x32_bf16 v[108:111], v[148:151], v[192:195], v[108:111]
	v_mfma_f32_16x16x32_bf16 v[104:107], v[156:159], v[192:195], v[104:107]
	v_mfma_f32_16x16x32_bf16 v[60:63], v[148:151], v[200:203], v[60:63]
	v_mfma_f32_16x16x32_bf16 v[56:59], v[156:159], v[200:203], v[56:59]
	v_mfma_f32_16x16x32_bf16 v[20:23], v[148:151], v[208:211], v[20:23]
	v_mfma_f32_16x16x32_bf16 v[16:19], v[156:159], v[208:211], v[16:19]
	v_mfma_f32_16x16x32_bf16 v[112:115], v[152:155], v[188:191], v[112:115]
	v_mfma_f32_16x16x32_bf16 v[116:119], v[160:163], v[188:191], v[116:119]
	v_mfma_f32_16x16x32_bf16 v[108:111], v[152:155], v[196:199], v[108:111]
	v_mfma_f32_16x16x32_bf16 v[104:107], v[160:163], v[196:199], v[104:107]
	v_mfma_f32_16x16x32_bf16 v[60:63], v[152:155], v[204:207], v[60:63]
	v_mfma_f32_16x16x32_bf16 v[56:59], v[160:163], v[204:207], v[56:59]
	v_mfma_f32_16x16x32_bf16 v[20:23], v[152:155], v[212:215], v[20:23]
	v_mfma_f32_16x16x32_bf16 v[16:19], v[160:163], v[212:215], v[16:19]
	s_setprio 0
	s_setprio 1
	v_mfma_f32_16x16x32_bf16 v[124:127], v[164:167], v[184:187], v[124:127]
	v_mfma_f32_16x16x32_bf16 v[120:123], v[172:175], v[184:187], v[120:123]
	v_mfma_f32_16x16x32_bf16 v[84:87], v[164:167], v[192:195], v[84:87]
	v_mfma_f32_16x16x32_bf16 v[80:83], v[172:175], v[192:195], v[80:83]
	v_mfma_f32_16x16x32_bf16 v[36:39], v[164:167], v[200:203], v[36:39]
	v_mfma_f32_16x16x32_bf16 v[32:35], v[172:175], v[200:203], v[32:35]
	v_mfma_f32_16x16x32_bf16 v[4:7], v[164:167], v[208:211], v[4:7]
	v_mfma_f32_16x16x32_bf16 v[0:3], v[172:175], v[208:211], v[0:3]
	v_mfma_f32_16x16x32_bf16 v[124:127], v[168:171], v[188:191], v[124:127]
	v_mfma_f32_16x16x32_bf16 v[120:123], v[180:183], v[188:191], v[120:123]
	v_mfma_f32_16x16x32_bf16 v[84:87], v[168:171], v[196:199], v[84:87]
	v_mfma_f32_16x16x32_bf16 v[80:83], v[180:183], v[196:199], v[80:83]
	v_mfma_f32_16x16x32_bf16 v[36:39], v[168:171], v[204:207], v[36:39]
	v_mfma_f32_16x16x32_bf16 v[32:35], v[180:183], v[204:207], v[32:35]
	v_mfma_f32_16x16x32_bf16 v[4:7], v[168:171], v[212:215], v[4:7]
	v_mfma_f32_16x16x32_bf16 v[0:3], v[180:183], v[212:215], v[0:3]
	s_setprio 0
	s_barrier
	s_add_i32 s57, s57, 2
	s_add_u32 s0, s0, 0x100
	s_addc_u32 s1, s1, 0
	s_add_u32 s9, s9, 0x100
	s_addc_u32 s56, s56, 0
	s_cmp_gt_u32 s57, 13
	s_cbranch_scc0 .LBB0_701
	s_lshl_b32 s54, s10, 8
	s_mul_i32 s0, s8, 0x240000
	s_ashr_i32 s55, s54, 31
	s_mul_hi_i32 s1, s8, 0x240000
	s_add_u32 s0, s0, s54
	s_addc_u32 s1, s1, s55
	s_lshl_b64 s[0:1], s[0:1], 1
	s_add_u32 s48, s16, s0
	s_addc_u32 s49, s17, s1
	s_add_i32 s78, s78, 1
	s_mul_i32 s0, s78, s65
	s_mul_hi_u32 s1, s78, s3
	s_add_i32 s1, s1, s0
	s_mul_i32 s0, s78, s3
	s_add_u32 s56, s0, s2
	s_addc_u32 s57, s1, s15
	s_mov_b32 s9, s8
	v_mov_b32_e32 v136, v141
	v_lshl_add_u64 v[148:149], s[48:49], 0, v[136:137]
	v_add_co_u32_e32 v148, vcc, s42, v148
	s_mov_b32 s85, 0
	s_nop 0
	v_addc_co_u32_e32 v149, vcc, 0, v149, vcc
	global_load_dwordx4 v[180:183], v[148:149], off offset:2048
	s_mov_b32 s84, 0x100
	v_lshl_add_u64 v[150:151], v[148:149], 0, s[84:85]
	global_load_dwordx4 v[184:187], v[150:151], off offset:2048
	s_mov_b32 s84, 0x48000
	v_lshl_add_u64 v[152:153], v[148:149], 0, s[84:85]
	global_load_dwordx4 v[188:191], v[152:153], off offset:2048
	s_mov_b32 s84, 0x48100
	v_lshl_add_u64 v[150:151], v[148:149], 0, s[84:85]
	global_load_dwordx4 v[192:195], v[150:151], off offset:2048
	s_mov_b32 s84, 0x90000
	v_lshl_add_u64 v[152:153], v[148:149], 0, s[84:85]
	global_load_dwordx4 v[196:199], v[152:153], off offset:2048
	s_mov_b32 s84, 0x90100
	v_lshl_add_u64 v[150:151], v[148:149], 0, s[84:85]
	global_load_dwordx4 v[200:203], v[150:151], off offset:2048
	s_mov_b32 s84, 0xd8000
	v_lshl_add_u64 v[152:153], v[148:149], 0, s[84:85]
	global_load_dwordx4 v[204:207], v[152:153], off offset:2048
	s_mov_b32 s84, 0xd8100
	v_lshl_add_u64 v[150:151], v[148:149], 0, s[84:85]
	global_load_dwordx4 v[208:211], v[150:151], off offset:2048
	s_mov_b32 s84, 0x240000
	v_lshl_add_u64 v[152:153], v[148:149], 0, s[84:85]
	global_load_dwordx4 v[212:215], v[152:153], off offset:2048
	s_mov_b32 s84, 0x240100
	v_lshl_add_u64 v[150:151], v[148:149], 0, s[84:85]
	global_load_dwordx4 v[216:219], v[150:151], off offset:2048
	s_mov_b32 s84, 0x288000
	v_lshl_add_u64 v[152:153], v[148:149], 0, s[84:85]
	global_load_dwordx4 v[224:227], v[152:153], off offset:2048
	s_mov_b32 s84, 0x288100
	v_lshl_add_u64 v[150:151], v[148:149], 0, s[84:85]
	global_load_dwordx4 v[228:231], v[150:151], off offset:2048
	s_mov_b32 s84, 0x2d0000
	v_lshl_add_u64 v[152:153], v[148:149], 0, s[84:85]
	global_load_dwordx4 v[232:235], v[152:153], off offset:2048
	s_mov_b32 s84, 0x2d0100
	v_lshl_add_u64 v[150:151], v[148:149], 0, s[84:85]
	global_load_dwordx4 v[236:239], v[150:151], off offset:2048
	s_mov_b32 s84, 0x318000
	v_lshl_add_u64 v[152:153], v[148:149], 0, s[84:85]
	global_load_dwordx4 v[240:243], v[152:153], off offset:2048
	s_mov_b32 s84, 0x318100
	v_lshl_add_u64 v[150:151], v[148:149], 0, s[84:85]
	global_load_dwordx4 v[244:247], v[150:151], off offset:2048
	s_waitcnt vmcnt(15)
;     ...
; #pragma unroll
;                 for (int bj = 0; bj < NBJ; ++bj) {
;                     const unsigned off = lo_ + (unsigned)(((ai * 128 + m * 16) * PLD + bj * 128) * 2);
;                     const u32x4 rv = *(const u32x4*)(pb + off + PC_GA * 2);
;                     acc[ai][bj][m][0][0] *= bflo(rv[0]); acc[ai][bj][m][0][1] *= bfhi(rv[0]); acc[ai][bj][m][0][2] *= bflo(rv[1]); acc[ai][bj][m][0][3] *= bfhi(rv[1]);
;                     acc[ai][bj][m][1][0] *= bflo(rv[2]); acc[ai][bj][m][1][1] *= bfhi(rv[2]); acc[ai][bj][m][1][2] *= bflo(rv[3]); acc[ai][bj][m][1][3] *= bfhi(rv[3]);
;                     asm volatile("" : "+v"(acc[ai][bj][m][0]), "+v"(acc[ai][bj][m][1]) :: "memory");
	v_lshlrev_b32_e32 v148, 16, v180
	v_and_b32_e32 v149, 0xffff0000, v180
	v_pk_mul_f32 v[8:9], v[8:9], v[148:149]
	v_lshlrev_b32_e32 v150, 16, v181
	v_and_b32_e32 v151, 0xffff0000, v181
	v_pk_mul_f32 v[10:11], v[10:11], v[150:151]
	v_lshlrev_b32_e32 v148, 16, v182
	v_and_b32_e32 v149, 0xffff0000, v182
	v_pk_mul_f32 v[12:13], v[12:13], v[148:149]
	v_lshlrev_b32_e32 v150, 16, v183
	v_and_b32_e32 v151, 0xffff0000, v183
	v_pk_mul_f32 v[14:15], v[14:15], v[150:151]
	s_waitcnt vmcnt(14)
	v_lshlrev_b32_e32 v148, 16, v184
	v_and_b32_e32 v149, 0xffff0000, v184
	v_pk_mul_f32 v[28:29], v[28:29], v[148:149]
	v_lshlrev_b32_e32 v150, 16, v185
	v_and_b32_e32 v151, 0xffff0000, v185
	v_pk_mul_f32 v[30:31], v[30:31], v[150:151]
	v_lshlrev_b32_e32 v148, 16, v186
	v_and_b32_e32 v149, 0xffff0000, v186
	v_pk_mul_f32 v[24:25], v[24:25], v[148:149]
	v_lshlrev_b32_e32 v150, 16, v187
	v_and_b32_e32 v151, 0xffff0000, v187
	v_pk_mul_f32 v[26:27], v[26:27], v[150:151]
	s_waitcnt vmcnt(13)
	v_lshlrev_b32_e32 v148, 16, v188
	v_and_b32_e32 v149, 0xffff0000, v188
	v_pk_mul_f32 v[40:41], v[40:41], v[148:149]
	v_lshlrev_b32_e32 v150, 16, v189
	v_and_b32_e32 v151, 0xffff0000, v189
	v_pk_mul_f32 v[42:43], v[42:43], v[150:151]
	v_lshlrev_b32_e32 v148, 16, v190
	v_and_b32_e32 v149, 0xffff0000, v190
	v_pk_mul_f32 v[44:45], v[44:45], v[148:149]
	v_lshlrev_b32_e32 v150, 16, v191
	v_and_b32_e32 v151, 0xffff0000, v191
	v_pk_mul_f32 v[46:47], v[46:47], v[150:151]
	s_waitcnt vmcnt(12)
	v_lshlrev_b32_e32 v148, 16, v192
	v_and_b32_e32 v149, 0xffff0000, v192
	v_pk_mul_f32 v[48:49], v[48:49], v[148:149]
	v_lshlrev_b32_e32 v150, 16, v193
	v_and_b32_e32 v151, 0xffff0000, v193
	v_pk_mul_f32 v[50:51], v[50:51], v[150:151]
	v_lshlrev_b32_e32 v148, 16, v194
	v_and_b32_e32 v149, 0xffff0000, v194
	v_pk_mul_f32 v[52:53], v[52:53], v[148:149]
	v_lshlrev_b32_e32 v150, 16, v195
	v_and_b32_e32 v151, 0xffff0000, v195
	v_pk_mul_f32 v[54:55], v[54:55], v[150:151]
	s_waitcnt vmcnt(11)
	v_lshlrev_b32_e32 v148, 16, v196
	v_and_b32_e32 v149, 0xffff0000, v196
	v_pk_mul_f32 v[64:65], v[64:65], v[148:149]
	v_lshlrev_b32_e32 v150, 16, v197
	v_and_b32_e32 v151, 0xffff0000, v197
	v_pk_mul_f32 v[66:67], v[66:67], v[150:151]
	v_lshlrev_b32_e32 v148, 16, v198
	v_and_b32_e32 v149, 0xffff0000, v198
	v_pk_mul_f32 v[68:69], v[68:69], v[148:149]
	v_lshlrev_b32_e32 v150, 16, v199
	v_and_b32_e32 v151, 0xffff0000, v199
	v_pk_mul_f32 v[70:71], v[70:71], v[150:151]
	s_waitcnt vmcnt(10)
	v_lshlrev_b32_e32 v148, 16, v200
	v_and_b32_e32 v149, 0xffff0000, v200
	v_pk_mul_f32 v[72:73], v[72:73], v[148:149]
	v_lshlrev_b32_e32 v150, 16, v201
	v_and_b32_e32 v151, 0xffff0000, v201
	v_pk_mul_f32 v[74:75], v[74:75], v[150:151]
	v_lshlrev_b32_e32 v148, 16, v202
	v_and_b32_e32 v149, 0xffff0000, v202
	v_pk_mul_f32 v[76:77], v[76:77], v[148:149]
	v_lshlrev_b32_e32 v150, 16, v203
	v_and_b32_e32 v151, 0xffff0000, v203
	v_pk_mul_f32 v[78:79], v[78:79], v[150:151]
	s_waitcnt vmcnt(9)
	v_lshlrev_b32_e32 v148, 16, v204
	v_and_b32_e32 v149, 0xffff0000, v204
	v_pk_mul_f32 v[88:89], v[88:89], v[148:149]
	v_lshlrev_b32_e32 v150, 16, v205
	v_and_b32_e32 v151, 0xffff0000, v205
	v_pk_mul_f32 v[90:91], v[90:91], v[150:151]
	v_lshlrev_b32_e32 v148, 16, v206
	v_and_b32_e32 v149, 0xffff0000, v206
	v_pk_mul_f32 v[92:93], v[92:93], v[148:149]
	v_lshlrev_b32_e32 v150, 16, v207
	v_and_b32_e32 v151, 0xffff0000, v207
	v_pk_mul_f32 v[94:95], v[94:95], v[150:151]
	s_waitcnt vmcnt(8)
	v_lshlrev_b32_e32 v148, 16, v208
	v_and_b32_e32 v149, 0xffff0000, v208
	v_pk_mul_f32 v[96:97], v[96:97], v[148:149]
	v_lshlrev_b32_e32 v150, 16, v209
	v_and_b32_e32 v151, 0xffff0000, v209
	v_pk_mul_f32 v[98:99], v[98:99], v[150:151]
	v_lshlrev_b32_e32 v148, 16, v210
	v_and_b32_e32 v149, 0xffff0000, v210
	v_pk_mul_f32 v[100:101], v[100:101], v[148:149]
	v_lshlrev_b32_e32 v150, 16, v211
	v_and_b32_e32 v151, 0xffff0000, v211
	v_pk_mul_f32 v[102:103], v[102:103], v[150:151]
	s_waitcnt vmcnt(7)
	v_lshlrev_b32_e32 v148, 16, v212
	v_and_b32_e32 v149, 0xffff0000, v212
	v_pk_mul_f32 v[112:113], v[112:113], v[148:149]
	v_lshlrev_b32_e32 v150, 16, v213
	v_and_b32_e32 v151, 0xffff0000, v213
	v_pk_mul_f32 v[114:115], v[114:115], v[150:151]
	v_lshlrev_b32_e32 v148, 16, v214
	v_and_b32_e32 v149, 0xffff0000, v214
	v_pk_mul_f32 v[116:117], v[116:117], v[148:149]
	v_lshlrev_b32_e32 v150, 16, v215
	v_and_b32_e32 v151, 0xffff0000, v215
	v_pk_mul_f32 v[118:119], v[118:119], v[150:151]
	s_waitcnt vmcnt(6)
;     __device__ bool next(int i, Unit& u) const {
;         const long L = (long)i * G + c; if (L >= lim) return false;
;         unit_of((int)L, u); return true;
;     ...
;                     acc[ai][bj][m][0][0] *= bflo(rv[0]); acc[ai][bj][m][0][1] *= bfhi(rv[0]); acc[ai][bj][m][0][2] *= bflo(rv[1]); acc[ai][bj][m][0][3] *= bfhi(rv[1]);
;                     acc[ai][bj][m][1][0] *= bflo(rv[2]); acc[ai][bj][m][1][1] *= bfhi(rv[2]); acc[ai][bj][m][1][2] *= bflo(rv[3]); acc[ai][bj][m][1][3] *= bfhi(rv[3]);
;                     asm volatile("" : "+v"(acc[ai][bj][m][0]), "+v"(acc[ai][bj][m][1]) :: "memory");
	v_lshlrev_b32_e32 v148, 16, v216
	v_and_b32_e32 v149, 0xffff0000, v216
	v_pk_mul_f32 v[124:125], v[124:125], v[148:149]
	v_lshlrev_b32_e32 v150, 16, v217
	v_and_b32_e32 v151, 0xffff0000, v217
	v_pk_mul_f32 v[126:127], v[126:127], v[150:151]
	v_lshlrev_b32_e32 v148, 16, v218
	v_and_b32_e32 v149, 0xffff0000, v218
	v_pk_mul_f32 v[120:121], v[120:121], v[148:149]
	v_lshlrev_b32_e32 v150, 16, v219
	v_and_b32_e32 v151, 0xffff0000, v219
	v_pk_mul_f32 v[122:123], v[122:123], v[150:151]
	s_waitcnt vmcnt(5)
	v_lshlrev_b32_e32 v148, 16, v224
	v_and_b32_e32 v149, 0xffff0000, v224
	v_pk_mul_f32 v[108:109], v[108:109], v[148:149]
	v_lshlrev_b32_e32 v150, 16, v225
	v_and_b32_e32 v151, 0xffff0000, v225
	v_pk_mul_f32 v[110:111], v[110:111], v[150:151]
	v_lshlrev_b32_e32 v148, 16, v226
	v_and_b32_e32 v149, 0xffff0000, v226
	v_pk_mul_f32 v[104:105], v[104:105], v[148:149]
	v_lshlrev_b32_e32 v150, 16, v227
	v_and_b32_e32 v151, 0xffff0000, v227
	v_pk_mul_f32 v[106:107], v[106:107], v[150:151]
	s_waitcnt vmcnt(4)
	v_lshlrev_b32_e32 v148, 16, v228
	v_and_b32_e32 v149, 0xffff0000, v228
	v_pk_mul_f32 v[84:85], v[84:85], v[148:149]
	v_lshlrev_b32_e32 v150, 16, v229
	v_and_b32_e32 v151, 0xffff0000, v229
	v_pk_mul_f32 v[86:87], v[86:87], v[150:151]
	v_lshlrev_b32_e32 v148, 16, v230
	v_and_b32_e32 v149, 0xffff0000, v230
	v_pk_mul_f32 v[80:81], v[80:81], v[148:149]
	v_lshlrev_b32_e32 v150, 16, v231
	v_and_b32_e32 v151, 0xffff0000, v231
	v_pk_mul_f32 v[82:83], v[82:83], v[150:151]
	s_waitcnt vmcnt(3)
	v_lshlrev_b32_e32 v148, 16, v232
	v_and_b32_e32 v149, 0xffff0000, v232
	v_pk_mul_f32 v[60:61], v[60:61], v[148:149]
	v_lshlrev_b32_e32 v150, 16, v233
	v_and_b32_e32 v151, 0xffff0000, v233
	v_pk_mul_f32 v[62:63], v[62:63], v[150:151]
	v_lshlrev_b32_e32 v148, 16, v234
	v_and_b32_e32 v149, 0xffff0000, v234
	v_pk_mul_f32 v[56:57], v[56:57], v[148:149]
	v_lshlrev_b32_e32 v150, 16, v235
	v_and_b32_e32 v151, 0xffff0000, v235
	v_pk_mul_f32 v[58:59], v[58:59], v[150:151]
	s_waitcnt vmcnt(2)
	v_lshlrev_b32_e32 v148, 16, v236
	v_and_b32_e32 v149, 0xffff0000, v236
	v_pk_mul_f32 v[36:37], v[36:37], v[148:149]
	v_lshlrev_b32_e32 v150, 16, v237
	v_and_b32_e32 v151, 0xffff0000, v237
	v_pk_mul_f32 v[38:39], v[38:39], v[150:151]
	v_lshlrev_b32_e32 v148, 16, v238
	v_and_b32_e32 v149, 0xffff0000, v238
	v_pk_mul_f32 v[32:33], v[32:33], v[148:149]
	v_lshlrev_b32_e32 v150, 16, v239
	v_and_b32_e32 v151, 0xffff0000, v239
	v_pk_mul_f32 v[34:35], v[34:35], v[150:151]
	s_waitcnt vmcnt(1)
	v_lshlrev_b32_e32 v148, 16, v240
	v_and_b32_e32 v149, 0xffff0000, v240
	v_pk_mul_f32 v[20:21], v[20:21], v[148:149]
	v_lshlrev_b32_e32 v150, 16, v241
	v_and_b32_e32 v151, 0xffff0000, v241
	v_pk_mul_f32 v[22:23], v[22:23], v[150:151]
	v_lshlrev_b32_e32 v148, 16, v242
	v_and_b32_e32 v149, 0xffff0000, v242
	v_pk_mul_f32 v[16:17], v[16:17], v[148:149]
	v_lshlrev_b32_e32 v150, 16, v243
	v_and_b32_e32 v151, 0xffff0000, v243
	v_pk_mul_f32 v[18:19], v[18:19], v[150:151]
	s_waitcnt vmcnt(0)
	v_lshlrev_b32_e32 v148, 16, v244
	v_and_b32_e32 v149, 0xffff0000, v244
	v_pk_mul_f32 v[4:5], v[4:5], v[148:149]
	v_lshlrev_b32_e32 v150, 16, v245
	v_and_b32_e32 v151, 0xffff0000, v245
	v_pk_mul_f32 v[6:7], v[6:7], v[150:151]
	v_lshlrev_b32_e32 v148, 16, v246
	v_and_b32_e32 v149, 0xffff0000, v246
	v_pk_mul_f32 v[0:1], v[0:1], v[148:149]
	v_lshlrev_b32_e32 v150, 16, v247
	v_and_b32_e32 v151, 0xffff0000, v247
	v_pk_mul_f32 v[2:3], v[2:3], v[150:151]
	v_mov_b64_e32 v[148:149], s[6:7]
	v_cmp_ge_i64_e32 vcc, s[56:57], v[148:149]
	v_cmp_lt_i64_e64 s[0:1], s[56:57], v[148:149]
	s_cbranch_vccnz .LBB0_704
	s_ashr_i32 s9, s56, 31
	s_lshr_b32 s9, s9, 29
	s_add_i32 s9, s56, s9
	s_ashr_i32 s10, s9, 3
	s_and_b32 s9, s9, -8
	s_sub_i32 s9, s56, s9
	s_cmp_lt_i32 s9, 0
	s_cselect_b32 s34, s33, 0x44
	s_mul_i32 s9, s9, s34
	s_add_i32 s9, s9, s10
	s_ashr_i32 s10, s9, 31
	s_lshr_b32 s10, s10, 26
	s_add_i32 s10, s9, s10
	s_ashr_i32 s34, s10, 6
	s_lshl_b32 s34, s34, 3
	s_sub_i32 s35, 0x44, s34
	s_min_i32 s35, s35, 8
	s_abs_i32 s56, s35
	v_cvt_f32_u32_e32 v136, s56
	s_sub_i32 s58, 0, s56
	s_andn2_b32 s10, s10, 63
	s_sub_i32 s9, s9, s10
	v_rcp_iflag_f32_e32 v136, v136
	s_abs_i32 s10, s9
	s_xor_b32 s57, s9, s35
	s_ashr_i32 s57, s57, 31
	v_mul_f32_e32 v136, 0x4f7ffffe, v136
	v_cvt_u32_f32_e32 v136, v136
	s_nop 0
	v_readfirstlane_b32 s59, v136
	s_mul_i32 s58, s58, s59
	s_mul_hi_u32 s58, s59, s58
	s_add_i32 s59, s59, s58
	s_mul_hi_u32 s58, s10, s59
	s_mul_i32 s59, s58, s56
	s_sub_i32 s10, s10, s59
	s_add_i32 s60, s58, 1
	s_sub_i32 s59, s10, s56
	s_cmp_ge_u32 s10, s56
	s_cselect_b32 s58, s60, s58
	s_cselect_b32 s10, s59, s10
	s_add_i32 s59, s58, 1
	s_cmp_ge_u32 s10, s56
	s_cselect_b32 s10, s59, s58
	s_xor_b32 s10, s10, s57
	s_sub_i32 s10, s10, s57
	s_mul_i32 s35, s10, s35
	s_sub_i32 s9, s9, s35
	s_add_i32 s9, s34, s9

.LBB0_705:
	ds_read_b128 v[148:151], v144
	ds_read_b128 v[152:155], v144 offset:1024
	ds_read_b128 v[156:159], v144 offset:2048
	ds_read_b128 v[160:163], v144 offset:3072
	ds_read_b128 v[164:167], v145
	ds_read_b128 v[168:171], v145 offset:1024
	ds_read_b128 v[172:175], v145 offset:2048
	ds_read_b128 v[180:183], v145 offset:3072
	ds_read_b128 v[184:187], v146
	ds_read_b128 v[188:191], v146 offset:1024
	ds_read_b128 v[192:195], v146 offset:2048
	ds_read_b128 v[196:199], v146 offset:3072
	ds_read_b128 v[200:203], v146 offset:4096
	ds_read_b128 v[204:207], v146 offset:5120
	ds_read_b128 v[208:211], v146 offset:6144
	ds_read_b128 v[212:215], v146 offset:7168
	s_add_u32 s52, s50, 0xfff80080
	s_addc_u32 s53, s51, -1
	s_cmp_eq_u32 s85, 12
	s_cselect_b32 s63, s9, s53
	s_cselect_b32 s62, s34, s52
	s_cselect_b32 s53, s11, s84
	s_cselect_b32 s52, s35, s79
	s_mov_b32 m0, s66
	v_lshl_add_u64 v[216:217], s[50:51], 0, v[128:129]
	global_load_lds_dwordx4 v[216:217], off
	v_lshl_add_u64 v[216:217], s[50:51], 0, v[132:133]
	s_mov_b32 m0, s67
	s_nop 0
	global_load_lds_dwordx4 v[216:217], off
	s_waitcnt vmcnt(8)
	s_waitcnt lgkmcnt(0)
	s_barrier
	s_setprio 1
	s_waitcnt lgkmcnt(0)
	v_mfma_f32_16x16x32_bf16 v[8:11], v[148:151], v[184:187], v[8:11]
	v_mfma_f32_16x16x32_bf16 v[12:15], v[156:159], v[184:187], v[12:15]
	v_mfma_f32_16x16x32_bf16 v[40:43], v[148:151], v[192:195], v[40:43]
	v_mfma_f32_16x16x32_bf16 v[44:47], v[156:159], v[192:195], v[44:47]
	v_mfma_f32_16x16x32_bf16 v[64:67], v[148:151], v[200:203], v[64:67]
	v_mfma_f32_16x16x32_bf16 v[68:71], v[156:159], v[200:203], v[68:71]
	v_mfma_f32_16x16x32_bf16 v[88:91], v[148:151], v[208:211], v[88:91]
	v_mfma_f32_16x16x32_bf16 v[92:95], v[156:159], v[208:211], v[92:95]
	v_mfma_f32_16x16x32_bf16 v[8:11], v[152:155], v[188:191], v[8:11]
	v_mfma_f32_16x16x32_bf16 v[12:15], v[160:163], v[188:191], v[12:15]
	v_mfma_f32_16x16x32_bf16 v[40:43], v[152:155], v[196:199], v[40:43]
	v_mfma_f32_16x16x32_bf16 v[44:47], v[160:163], v[196:199], v[44:47]
	v_mfma_f32_16x16x32_bf16 v[64:67], v[152:155], v[204:207], v[64:67]
	v_mfma_f32_16x16x32_bf16 v[68:71], v[160:163], v[204:207], v[68:71]
	v_mfma_f32_16x16x32_bf16 v[88:91], v[152:155], v[212:215], v[88:91]
	v_mfma_f32_16x16x32_bf16 v[92:95], v[160:163], v[212:215], v[92:95]
	s_setprio 0
	s_setprio 1
	v_mfma_f32_16x16x32_bf16 v[28:31], v[164:167], v[184:187], v[28:31]
	v_mfma_f32_16x16x32_bf16 v[24:27], v[172:175], v[184:187], v[24:27]
	v_mfma_f32_16x16x32_bf16 v[48:51], v[164:167], v[192:195], v[48:51]
	v_mfma_f32_16x16x32_bf16 v[52:55], v[172:175], v[192:195], v[52:55]
	v_mfma_f32_16x16x32_bf16 v[72:75], v[164:167], v[200:203], v[72:75]
	v_mfma_f32_16x16x32_bf16 v[76:79], v[172:175], v[200:203], v[76:79]
	v_mfma_f32_16x16x32_bf16 v[96:99], v[164:167], v[208:211], v[96:99]
	v_mfma_f32_16x16x32_bf16 v[100:103], v[172:175], v[208:211], v[100:103]
	v_mfma_f32_16x16x32_bf16 v[28:31], v[168:171], v[188:191], v[28:31]
	v_mfma_f32_16x16x32_bf16 v[24:27], v[180:183], v[188:191], v[24:27]
	v_mfma_f32_16x16x32_bf16 v[48:51], v[168:171], v[196:199], v[48:51]
	v_mfma_f32_16x16x32_bf16 v[52:55], v[180:183], v[196:199], v[52:55]
	v_mfma_f32_16x16x32_bf16 v[72:75], v[168:171], v[204:207], v[72:75]
	v_mfma_f32_16x16x32_bf16 v[76:79], v[180:183], v[204:207], v[76:79]
	v_mfma_f32_16x16x32_bf16 v[96:99], v[168:171], v[212:215], v[96:99]
	v_mfma_f32_16x16x32_bf16 v[100:103], v[180:183], v[212:215], v[100:103]
	s_setprio 0
	s_barrier
	ds_read_b128 v[184:187], v146 offset:16384
	ds_read_b128 v[188:191], v146 offset:17408
	ds_read_b128 v[192:195], v146 offset:18432
	ds_read_b128 v[196:199], v146 offset:19456
	ds_read_b128 v[200:203], v146 offset:20480
	ds_read_b128 v[204:207], v146 offset:21504
	ds_read_b128 v[208:211], v146 offset:22528
	ds_read_b128 v[212:215], v146 offset:23552
	s_mov_b32 m0, s72
	v_lshl_add_u64 v[216:217], s[52:53], 0, v[130:131]
	s_add_u32 s86, s52, 0x80000
	global_load_lds_dwordx4 v[216:217], off
	v_lshl_add_u64 v[218:219], s[52:53], 0, v[134:135]
	s_mov_b32 m0, s73
	s_addc_u32 s87, s53, 0
	global_load_lds_dwordx4 v[218:219], off
	v_lshl_add_u64 v[222:223], s[86:87], 0, v[130:131]
	s_mov_b32 m0, s74
	v_lshl_add_u64 v[224:225], s[62:63], 0, v[132:133]
	global_load_lds_dwordx4 v[222:223], off
	v_lshl_add_u64 v[222:223], s[86:87], 0, v[134:135]
	s_mov_b32 m0, s76
	s_nop 0
	global_load_lds_dwordx4 v[222:223], off
	v_lshl_add_u64 v[222:223], s[62:63], 0, v[128:129]
	s_mov_b32 m0, s36
	s_nop 0
	global_load_lds_dwordx4 v[222:223], off
	s_mov_b32 m0, s37
	s_nop 0
	global_load_lds_dwordx4 v[224:225], off
	s_waitcnt vmcnt(8)
	s_waitcnt lgkmcnt(0)
	s_barrier
	s_setprio 1
	s_waitcnt lgkmcnt(0)
	v_mfma_f32_16x16x32_bf16 v[112:115], v[148:151], v[184:187], v[112:115]
	v_mfma_f32_16x16x32_bf16 v[116:119], v[156:159], v[184:187], v[116:119]
	v_mfma_f32_16x16x32_bf16 v[108:111], v[148:151], v[192:195], v[108:111]
	v_mfma_f32_16x16x32_bf16 v[104:107], v[156:159], v[192:195], v[104:107]
	v_mfma_f32_16x16x32_bf16 v[60:63], v[148:151], v[200:203], v[60:63]
	v_mfma_f32_16x16x32_bf16 v[56:59], v[156:159], v[200:203], v[56:59]
	v_mfma_f32_16x16x32_bf16 v[20:23], v[148:151], v[208:211], v[20:23]
	v_mfma_f32_16x16x32_bf16 v[16:19], v[156:159], v[208:211], v[16:19]
	v_mfma_f32_16x16x32_bf16 v[112:115], v[152:155], v[188:191], v[112:115]
	v_mfma_f32_16x16x32_bf16 v[116:119], v[160:163], v[188:191], v[116:119]
	v_mfma_f32_16x16x32_bf16 v[108:111], v[152:155], v[196:199], v[108:111]
	v_mfma_f32_16x16x32_bf16 v[104:107], v[160:163], v[196:199], v[104:107]
	v_mfma_f32_16x16x32_bf16 v[60:63], v[152:155], v[204:207], v[60:63]
	v_mfma_f32_16x16x32_bf16 v[56:59], v[160:163], v[204:207], v[56:59]
	v_mfma_f32_16x16x32_bf16 v[20:23], v[152:155], v[212:215], v[20:23]
	v_mfma_f32_16x16x32_bf16 v[16:19], v[160:163], v[212:215], v[16:19]
	s_setprio 0
	s_setprio 1
	v_mfma_f32_16x16x32_bf16 v[124:127], v[164:167], v[184:187], v[124:127]
	v_mfma_f32_16x16x32_bf16 v[120:123], v[172:175], v[184:187], v[120:123]
	v_mfma_f32_16x16x32_bf16 v[84:87], v[164:167], v[192:195], v[84:87]
	v_mfma_f32_16x16x32_bf16 v[80:83], v[172:175], v[192:195], v[80:83]
	v_mfma_f32_16x16x32_bf16 v[36:39], v[164:167], v[200:203], v[36:39]
	v_mfma_f32_16x16x32_bf16 v[32:35], v[172:175], v[200:203], v[32:35]
	v_mfma_f32_16x16x32_bf16 v[4:7], v[164:167], v[208:211], v[4:7]
	v_mfma_f32_16x16x32_bf16 v[0:3], v[172:175], v[208:211], v[0:3]
	v_mfma_f32_16x16x32_bf16 v[124:127], v[168:171], v[188:191], v[124:127]
	v_mfma_f32_16x16x32_bf16 v[120:123], v[180:183], v[188:191], v[120:123]
	v_mfma_f32_16x16x32_bf16 v[84:87], v[168:171], v[196:199], v[84:87]
	v_mfma_f32_16x16x32_bf16 v[80:83], v[180:183], v[196:199], v[80:83]
	v_mfma_f32_16x16x32_bf16 v[36:39], v[168:171], v[204:207], v[36:39]
	v_mfma_f32_16x16x32_bf16 v[32:35], v[180:183], v[204:207], v[32:35]
	v_mfma_f32_16x16x32_bf16 v[4:7], v[168:171], v[212:215], v[4:7]
	v_mfma_f32_16x16x32_bf16 v[0:3], v[180:183], v[212:215], v[0:3]
	s_setprio 0
	s_barrier
	ds_read_b128 v[148:151], v147
	ds_read_b128 v[152:155], v147 offset:1024
	ds_read_b128 v[156:159], v147 offset:2048
	ds_read_b128 v[160:163], v147 offset:3072
	ds_read_b128 v[164:167], v138
	ds_read_b128 v[168:171], v138 offset:1024
	ds_read_b128 v[172:175], v138 offset:2048
	ds_read_b128 v[180:183], v138 offset:3072
	ds_read_b128 v[184:187], v146 offset:32768
	ds_read_b128 v[188:191], v146 offset:33792
	ds_read_b128 v[192:195], v146 offset:34816
	ds_read_b128 v[196:199], v146 offset:35840
	ds_read_b128 v[200:203], v146 offset:36864
	ds_read_b128 v[204:207], v146 offset:37888
	ds_read_b128 v[208:211], v146 offset:38912
	ds_read_b128 v[212:215], v146 offset:39936
	s_add_u32 s62, s62, 0x80000
	s_addc_u32 s63, s63, 0
	s_mov_b32 m0, s40
	v_lshl_add_u64 v[226:227], s[62:63], 0, v[128:129]
	global_load_lds_dwordx4 v[226:227], off
	v_lshl_add_u64 v[226:227], s[62:63], 0, v[132:133]
	s_mov_b32 m0, s41
	s_nop 0
	global_load_lds_dwordx4 v[226:227], off
	s_waitcnt vmcnt(8)
	s_waitcnt lgkmcnt(0)
	s_barrier
	s_setprio 1
	s_waitcnt lgkmcnt(0)
	v_mfma_f32_16x16x32_bf16 v[8:11], v[148:151], v[184:187], v[8:11]
	v_mfma_f32_16x16x32_bf16 v[12:15], v[156:159], v[184:187], v[12:15]
	v_mfma_f32_16x16x32_bf16 v[40:43], v[148:151], v[192:195], v[40:43]
	v_mfma_f32_16x16x32_bf16 v[44:47], v[156:159], v[192:195], v[44:47]
	v_mfma_f32_16x16x32_bf16 v[64:67], v[148:151], v[200:203], v[64:67]
	v_mfma_f32_16x16x32_bf16 v[68:71], v[156:159], v[200:203], v[68:71]
	v_mfma_f32_16x16x32_bf16 v[88:91], v[148:151], v[208:211], v[88:91]
	v_mfma_f32_16x16x32_bf16 v[92:95], v[156:159], v[208:211], v[92:95]
	v_mfma_f32_16x16x32_bf16 v[8:11], v[152:155], v[188:191], v[8:11]
	v_mfma_f32_16x16x32_bf16 v[12:15], v[160:163], v[188:191], v[12:15]
	v_mfma_f32_16x16x32_bf16 v[40:43], v[152:155], v[196:199], v[40:43]
	v_mfma_f32_16x16x32_bf16 v[44:47], v[160:163], v[196:199], v[44:47]
	v_mfma_f32_16x16x32_bf16 v[64:67], v[152:155], v[204:207], v[64:67]
	v_mfma_f32_16x16x32_bf16 v[68:71], v[160:163], v[204:207], v[68:71]
	v_mfma_f32_16x16x32_bf16 v[88:91], v[152:155], v[212:215], v[88:91]
	v_mfma_f32_16x16x32_bf16 v[92:95], v[160:163], v[212:215], v[92:95]
	s_setprio 0
	s_setprio 1
	v_mfma_f32_16x16x32_bf16 v[28:31], v[164:167], v[184:187], v[28:31]
	v_mfma_f32_16x16x32_bf16 v[24:27], v[172:175], v[184:187], v[24:27]
	v_mfma_f32_16x16x32_bf16 v[48:51], v[164:167], v[192:195], v[48:51]
	v_mfma_f32_16x16x32_bf16 v[52:55], v[172:175], v[192:195], v[52:55]
	v_mfma_f32_16x16x32_bf16 v[72:75], v[164:167], v[200:203], v[72:75]
	v_mfma_f32_16x16x32_bf16 v[76:79], v[172:175], v[200:203], v[76:79]
	v_mfma_f32_16x16x32_bf16 v[96:99], v[164:167], v[208:211], v[96:99]
	v_mfma_f32_16x16x32_bf16 v[100:103], v[172:175], v[208:211], v[100:103]
	v_mfma_f32_16x16x32_bf16 v[28:31], v[168:171], v[188:191], v[28:31]
	v_mfma_f32_16x16x32_bf16 v[24:27], v[180:183], v[188:191], v[24:27]
	v_mfma_f32_16x16x32_bf16 v[48:51], v[168:171], v[196:199], v[48:51]
	v_mfma_f32_16x16x32_bf16 v[52:55], v[180:183], v[196:199], v[52:55]
	v_mfma_f32_16x16x32_bf16 v[72:75], v[168:171], v[204:207], v[72:75]
	v_mfma_f32_16x16x32_bf16 v[76:79], v[180:183], v[204:207], v[76:79]
	v_mfma_f32_16x16x32_bf16 v[96:99], v[168:171], v[212:215], v[96:99]
	v_mfma_f32_16x16x32_bf16 v[100:103], v[180:183], v[212:215], v[100:103]
	s_setprio 0
	s_barrier
; #define PG8_BAR __builtin_amdgcn_s_barrier()
; template <class Epi>
; __device__ __forceinline__ void gemm_phase(LAS unsigned char* lds, const Gemm g, const StaticOrder& S, const Epi& E) {
;     ...
;         if (wr == 0) PG8_BAR;
	ds_read_b128 v[184:187], v146 offset:49152
	ds_read_b128 v[188:191], v146 offset:50176
	ds_read_b128 v[192:195], v146 offset:51200
	ds_read_b128 v[196:199], v146 offset:52224
	ds_read_b128 v[200:203], v146 offset:53248
	ds_read_b128 v[204:207], v146 offset:54272
	ds_read_b128 v[208:211], v146 offset:55296
	ds_read_b128 v[212:215], v146 offset:56320
	s_mov_b32 m0, s80
	v_lshl_add_u64 v[216:217], v[216:217], 0, s[22:23]
	s_add_u32 s52, s52, 0x80080
	global_load_lds_dwordx4 v[216:217], off
	v_lshl_add_u64 v[216:217], v[218:219], 0, s[22:23]
	s_mov_b32 m0, s81
	s_addc_u32 s53, s53, 0
	global_load_lds_dwordx4 v[216:217], off
	v_lshl_add_u64 v[216:217], s[52:53], 0, v[130:131]
	s_mov_b32 m0, s82
	s_nop 0
	global_load_lds_dwordx4 v[216:217], off
	v_lshl_add_u64 v[216:217], s[52:53], 0, v[134:135]
	s_mov_b32 m0, s83
	s_nop 0
	global_load_lds_dwordx4 v[216:217], off
	v_lshl_add_u64 v[216:217], v[222:223], 0, s[22:23]
	s_mov_b32 m0, s43
	s_nop 0
	global_load_lds_dwordx4 v[216:217], off
	v_lshl_add_u64 v[216:217], v[224:225], 0, s[22:23]
	s_mov_b32 m0, s64
	s_nop 0
	global_load_lds_dwordx4 v[216:217], off
	s_waitcnt vmcnt(8)
	s_waitcnt lgkmcnt(0)
	s_barrier
	s_setprio 1
	s_waitcnt lgkmcnt(0)
	v_mfma_f32_16x16x32_bf16 v[112:115], v[148:151], v[184:187], v[112:115]
	v_mfma_f32_16x16x32_bf16 v[116:119], v[156:159], v[184:187], v[116:119]
	v_mfma_f32_16x16x32_bf16 v[108:111], v[148:151], v[192:195], v[108:111]
	v_mfma_f32_16x16x32_bf16 v[104:107], v[156:159], v[192:195], v[104:107]
	v_mfma_f32_16x16x32_bf16 v[60:63], v[148:151], v[200:203], v[60:63]
	v_mfma_f32_16x16x32_bf16 v[56:59], v[156:159], v[200:203], v[56:59]
	v_mfma_f32_16x16x32_bf16 v[20:23], v[148:151], v[208:211], v[20:23]
	v_mfma_f32_16x16x32_bf16 v[16:19], v[156:159], v[208:211], v[16:19]
	v_mfma_f32_16x16x32_bf16 v[112:115], v[152:155], v[188:191], v[112:115]
	v_mfma_f32_16x16x32_bf16 v[116:119], v[160:163], v[188:191], v[116:119]
	v_mfma_f32_16x16x32_bf16 v[108:111], v[152:155], v[196:199], v[108:111]
	v_mfma_f32_16x16x32_bf16 v[104:107], v[160:163], v[196:199], v[104:107]
	v_mfma_f32_16x16x32_bf16 v[60:63], v[152:155], v[204:207], v[60:63]
	v_mfma_f32_16x16x32_bf16 v[56:59], v[160:163], v[204:207], v[56:59]
	v_mfma_f32_16x16x32_bf16 v[20:23], v[152:155], v[212:215], v[20:23]
	v_mfma_f32_16x16x32_bf16 v[16:19], v[160:163], v[212:215], v[16:19]
	s_setprio 0
	s_setprio 1
	v_mfma_f32_16x16x32_bf16 v[124:127], v[164:167], v[184:187], v[124:127]
	v_mfma_f32_16x16x32_bf16 v[120:123], v[172:175], v[184:187], v[120:123]
	v_mfma_f32_16x16x32_bf16 v[84:87], v[164:167], v[192:195], v[84:87]
	v_mfma_f32_16x16x32_bf16 v[80:83], v[172:175], v[192:195], v[80:83]
	v_mfma_f32_16x16x32_bf16 v[36:39], v[164:167], v[200:203], v[36:39]
	v_mfma_f32_16x16x32_bf16 v[32:35], v[172:175], v[200:203], v[32:35]
	v_mfma_f32_16x16x32_bf16 v[4:7], v[164:167], v[208:211], v[4:7]
	v_mfma_f32_16x16x32_bf16 v[0:3], v[172:175], v[208:211], v[0:3]
	v_mfma_f32_16x16x32_bf16 v[124:127], v[168:171], v[188:191], v[124:127]
	v_mfma_f32_16x16x32_bf16 v[120:123], v[180:183], v[188:191], v[120:123]
	v_mfma_f32_16x16x32_bf16 v[84:87], v[168:171], v[196:199], v[84:87]
	v_mfma_f32_16x16x32_bf16 v[80:83], v[180:183], v[196:199], v[80:83]
	v_mfma_f32_16x16x32_bf16 v[36:39], v[168:171], v[204:207], v[36:39]
	v_mfma_f32_16x16x32_bf16 v[32:35], v[180:183], v[204:207], v[32:35]
	v_mfma_f32_16x16x32_bf16 v[4:7], v[168:171], v[212:215], v[4:7]
	v_mfma_f32_16x16x32_bf16 v[0:3], v[180:183], v[212:215], v[0:3]
	s_setprio 0
	s_barrier
	s_add_i32 s85, s85, 2
	s_add_u32 s79, s79, 0x100
	s_addc_u32 s84, s84, 0
	s_add_u32 s50, s50, 0x100
	s_addc_u32 s51, s51, 0
	s_cmp_gt_u32 s85, 13
	s_cbranch_scc0 .LBB0_705
	s_and_b64 vcc, exec, s[26:27]
	s_cbranch_vccz .LBB0_708
	s_barrier

.LBB0_807:
	ds_read_b128 v[138:141], v148
	ds_read_b128 v[152:155], v148 offset:1024
	ds_read_b128 v[156:159], v148 offset:2048
	ds_read_b128 v[160:163], v148 offset:3072
	ds_read_b128 v[164:167], v149
	ds_read_b128 v[168:171], v149 offset:1024
	ds_read_b128 v[172:175], v149 offset:2048
	ds_read_b128 v[180:183], v149 offset:3072
	ds_read_b128 v[184:187], v150
	ds_read_b128 v[188:191], v150 offset:1024
	ds_read_b128 v[192:195], v150 offset:2048
	ds_read_b128 v[196:199], v150 offset:3072
	ds_read_b128 v[200:203], v150 offset:4096
	ds_read_b128 v[204:207], v150 offset:5120
	ds_read_b128 v[208:211], v150 offset:6144
	ds_read_b128 v[212:215], v150 offset:7168
	s_add_u32 s34, s60, 0xfff80080
	s_addc_u32 s35, s61, -1
	s_cmp_eq_u32 s74, 28
	s_cselect_b32 s65, s51, s35
	s_cselect_b32 s64, s57, s34
	s_cselect_b32 s63, s49, s73
	s_cselect_b32 s62, s67, s72
	v_lshl_add_u64 v[216:217], s[60:61], 0, v[128:129]
	s_add_i32 m0, s15, 0xc000
	s_nop 0
	global_load_lds_dwordx4 v[216:217], off
	v_lshl_add_u64 v[216:217], s[60:61], 0, v[132:133]
	s_add_i32 m0, s15, 0xe000
	s_nop 0
	global_load_lds_dwordx4 v[216:217], off
	s_waitcnt vmcnt(8)
	s_waitcnt lgkmcnt(0)
	s_barrier
	s_setprio 1
	s_waitcnt lgkmcnt(0)
	v_mfma_f32_16x16x32_bf16 v[124:127], v[138:141], v[184:187], v[124:127]
	v_mfma_f32_16x16x32_bf16 v[120:123], v[156:159], v[184:187], v[120:123]
	v_mfma_f32_16x16x32_bf16 v[108:111], v[138:141], v[192:195], v[108:111]
	v_mfma_f32_16x16x32_bf16 v[104:107], v[156:159], v[192:195], v[104:107]
	v_mfma_f32_16x16x32_bf16 v[92:95], v[138:141], v[200:203], v[92:95]
	v_mfma_f32_16x16x32_bf16 v[88:91], v[156:159], v[200:203], v[88:91]
	v_mfma_f32_16x16x32_bf16 v[76:79], v[138:141], v[208:211], v[76:79]
	v_mfma_f32_16x16x32_bf16 v[72:75], v[156:159], v[208:211], v[72:75]
	v_mfma_f32_16x16x32_bf16 v[124:127], v[152:155], v[188:191], v[124:127]
	v_mfma_f32_16x16x32_bf16 v[120:123], v[160:163], v[188:191], v[120:123]
	v_mfma_f32_16x16x32_bf16 v[108:111], v[152:155], v[196:199], v[108:111]
	v_mfma_f32_16x16x32_bf16 v[104:107], v[160:163], v[196:199], v[104:107]
	v_mfma_f32_16x16x32_bf16 v[92:95], v[152:155], v[204:207], v[92:95]
	v_mfma_f32_16x16x32_bf16 v[88:91], v[160:163], v[204:207], v[88:91]
	v_mfma_f32_16x16x32_bf16 v[76:79], v[152:155], v[212:215], v[76:79]
	v_mfma_f32_16x16x32_bf16 v[72:75], v[160:163], v[212:215], v[72:75]
	s_setprio 0
	s_setprio 1
	v_mfma_f32_16x16x32_bf16 v[116:119], v[164:167], v[184:187], v[116:119]
	v_mfma_f32_16x16x32_bf16 v[112:115], v[172:175], v[184:187], v[112:115]
	v_mfma_f32_16x16x32_bf16 v[100:103], v[164:167], v[192:195], v[100:103]
	v_mfma_f32_16x16x32_bf16 v[96:99], v[172:175], v[192:195], v[96:99]
	v_mfma_f32_16x16x32_bf16 v[84:87], v[164:167], v[200:203], v[84:87]
	v_mfma_f32_16x16x32_bf16 v[80:83], v[172:175], v[200:203], v[80:83]
	v_mfma_f32_16x16x32_bf16 v[68:71], v[164:167], v[208:211], v[68:71]
	v_mfma_f32_16x16x32_bf16 v[64:67], v[172:175], v[208:211], v[64:67]
	v_mfma_f32_16x16x32_bf16 v[116:119], v[168:171], v[188:191], v[116:119]
	v_mfma_f32_16x16x32_bf16 v[112:115], v[180:183], v[188:191], v[112:115]
	v_mfma_f32_16x16x32_bf16 v[100:103], v[168:171], v[196:199], v[100:103]
	v_mfma_f32_16x16x32_bf16 v[96:99], v[180:183], v[196:199], v[96:99]
	v_mfma_f32_16x16x32_bf16 v[84:87], v[168:171], v[204:207], v[84:87]
	v_mfma_f32_16x16x32_bf16 v[80:83], v[180:183], v[204:207], v[80:83]
	v_mfma_f32_16x16x32_bf16 v[68:71], v[168:171], v[212:215], v[68:71]
	v_mfma_f32_16x16x32_bf16 v[64:67], v[180:183], v[212:215], v[64:67]
	s_setprio 0
	s_barrier
	ds_read_b128 v[184:187], v150 offset:16384
	ds_read_b128 v[188:191], v150 offset:17408
	ds_read_b128 v[192:195], v150 offset:18432
	ds_read_b128 v[196:199], v150 offset:19456
	ds_read_b128 v[200:203], v150 offset:20480
	ds_read_b128 v[204:207], v150 offset:21504
	ds_read_b128 v[208:211], v150 offset:22528
	ds_read_b128 v[212:215], v150 offset:23552
	s_add_i32 s34, s59, s14
	v_lshl_add_u64 v[216:217], s[62:63], 0, v[130:131]
	s_mov_b32 m0, s34
	s_nop 0
	global_load_lds_dwordx4 v[216:217], off
	s_add_i32 m0, s34, 0x2000
	s_add_u32 s34, s62, 0x80000
	v_lshl_add_u64 v[218:219], s[62:63], 0, v[134:135]
	s_addc_u32 s35, s63, 0
	s_add_i32 s75, s66, s14
	global_load_lds_dwordx4 v[218:219], off
	v_lshl_add_u64 v[222:223], s[34:35], 0, v[130:131]
	s_mov_b32 m0, s75
	v_lshl_add_u64 v[224:225], s[64:65], 0, v[132:133]
	global_load_lds_dwordx4 v[222:223], off
	v_lshl_add_u64 v[222:223], s[34:35], 0, v[134:135]
	s_add_i32 m0, s75, 0x2000
	s_nop 0
	global_load_lds_dwordx4 v[222:223], off
	v_lshl_add_u64 v[222:223], s[64:65], 0, v[128:129]
	s_mov_b32 m0, s15
	s_nop 0
	global_load_lds_dwordx4 v[222:223], off
	s_mov_b32 m0, s33
	s_nop 0
	global_load_lds_dwordx4 v[224:225], off
	s_waitcnt vmcnt(8)
	s_waitcnt lgkmcnt(0)
	s_barrier
	s_setprio 1
	s_waitcnt lgkmcnt(0)
	v_mfma_f32_16x16x32_bf16 v[60:63], v[138:141], v[184:187], v[60:63]
	v_mfma_f32_16x16x32_bf16 v[56:59], v[156:159], v[184:187], v[56:59]
	v_mfma_f32_16x16x32_bf16 v[44:47], v[138:141], v[192:195], v[44:47]
	v_mfma_f32_16x16x32_bf16 v[40:43], v[156:159], v[192:195], v[40:43]
	v_mfma_f32_16x16x32_bf16 v[28:31], v[138:141], v[200:203], v[28:31]
	v_mfma_f32_16x16x32_bf16 v[24:27], v[156:159], v[200:203], v[24:27]
	v_mfma_f32_16x16x32_bf16 v[12:15], v[138:141], v[208:211], v[12:15]
	v_mfma_f32_16x16x32_bf16 v[8:11], v[156:159], v[208:211], v[8:11]
	v_mfma_f32_16x16x32_bf16 v[60:63], v[152:155], v[188:191], v[60:63]
	v_mfma_f32_16x16x32_bf16 v[56:59], v[160:163], v[188:191], v[56:59]
	v_mfma_f32_16x16x32_bf16 v[44:47], v[152:155], v[196:199], v[44:47]
	v_mfma_f32_16x16x32_bf16 v[40:43], v[160:163], v[196:199], v[40:43]
	v_mfma_f32_16x16x32_bf16 v[28:31], v[152:155], v[204:207], v[28:31]
	v_mfma_f32_16x16x32_bf16 v[24:27], v[160:163], v[204:207], v[24:27]
	v_mfma_f32_16x16x32_bf16 v[12:15], v[152:155], v[212:215], v[12:15]
	v_mfma_f32_16x16x32_bf16 v[8:11], v[160:163], v[212:215], v[8:11]
	s_setprio 0
	s_setprio 1
	v_mfma_f32_16x16x32_bf16 v[52:55], v[164:167], v[184:187], v[52:55]
	v_mfma_f32_16x16x32_bf16 v[48:51], v[172:175], v[184:187], v[48:51]
	v_mfma_f32_16x16x32_bf16 v[36:39], v[164:167], v[192:195], v[36:39]
	v_mfma_f32_16x16x32_bf16 v[32:35], v[172:175], v[192:195], v[32:35]
	v_mfma_f32_16x16x32_bf16 v[20:23], v[164:167], v[200:203], v[20:23]
	v_mfma_f32_16x16x32_bf16 v[16:19], v[172:175], v[200:203], v[16:19]
	v_mfma_f32_16x16x32_bf16 v[4:7], v[164:167], v[208:211], v[4:7]
	v_mfma_f32_16x16x32_bf16 v[0:3], v[172:175], v[208:211], v[0:3]
	v_mfma_f32_16x16x32_bf16 v[52:55], v[168:171], v[188:191], v[52:55]
	v_mfma_f32_16x16x32_bf16 v[48:51], v[180:183], v[188:191], v[48:51]
	v_mfma_f32_16x16x32_bf16 v[36:39], v[168:171], v[196:199], v[36:39]
	v_mfma_f32_16x16x32_bf16 v[32:35], v[180:183], v[196:199], v[32:35]
	v_mfma_f32_16x16x32_bf16 v[20:23], v[168:171], v[204:207], v[20:23]
	v_mfma_f32_16x16x32_bf16 v[16:19], v[180:183], v[204:207], v[16:19]
	v_mfma_f32_16x16x32_bf16 v[4:7], v[168:171], v[212:215], v[4:7]
	v_mfma_f32_16x16x32_bf16 v[0:3], v[180:183], v[212:215], v[0:3]
	s_setprio 0
	s_barrier
	s_add_i32 s75, 0, 0x18000
	s_add_i32 s76, 0, 0x1c000
	v_add_u32_e32 v160, s75, v143
	v_add_u32_e32 v177, s76, v143
	ds_read_b128 v[138:141], v160
	ds_read_b128 v[152:155], v160 offset:1024
	ds_read_b128 v[156:159], v160 offset:2048
	ds_read_b128 v[160:163], v160 offset:3072
	ds_read_b128 v[164:167], v177
	ds_read_b128 v[168:171], v177 offset:1024
	ds_read_b128 v[172:175], v177 offset:2048
	ds_read_b128 v[180:183], v177 offset:3072
	ds_read_b128 v[184:187], v150 offset:32768
	ds_read_b128 v[188:191], v150 offset:33792
	ds_read_b128 v[192:195], v150 offset:34816
	ds_read_b128 v[196:199], v150 offset:35840
	ds_read_b128 v[200:203], v150 offset:36864
	ds_read_b128 v[204:207], v150 offset:37888
	ds_read_b128 v[208:211], v150 offset:38912
	ds_read_b128 v[212:215], v150 offset:39936
	s_add_u32 s34, s64, 0x80000
	s_addc_u32 s35, s65, 0
	s_mov_b32 m0, s36
	v_lshl_add_u64 v[226:227], s[34:35], 0, v[128:129]
	global_load_lds_dwordx4 v[226:227], off
	v_lshl_add_u64 v[226:227], s[34:35], 0, v[132:133]
	s_mov_b32 m0, s37
	s_nop 0
	global_load_lds_dwordx4 v[226:227], off
	s_waitcnt vmcnt(8)
	s_waitcnt lgkmcnt(0)
	s_barrier
	s_setprio 1
	s_waitcnt lgkmcnt(0)
	v_mfma_f32_16x16x32_bf16 v[124:127], v[138:141], v[184:187], v[124:127]
	v_mfma_f32_16x16x32_bf16 v[120:123], v[156:159], v[184:187], v[120:123]
	v_mfma_f32_16x16x32_bf16 v[108:111], v[138:141], v[192:195], v[108:111]
	v_mfma_f32_16x16x32_bf16 v[104:107], v[156:159], v[192:195], v[104:107]
	v_mfma_f32_16x16x32_bf16 v[92:95], v[138:141], v[200:203], v[92:95]
	v_mfma_f32_16x16x32_bf16 v[88:91], v[156:159], v[200:203], v[88:91]
	v_mfma_f32_16x16x32_bf16 v[76:79], v[138:141], v[208:211], v[76:79]
	v_mfma_f32_16x16x32_bf16 v[72:75], v[156:159], v[208:211], v[72:75]
	v_mfma_f32_16x16x32_bf16 v[124:127], v[152:155], v[188:191], v[124:127]
	v_mfma_f32_16x16x32_bf16 v[120:123], v[160:163], v[188:191], v[120:123]
	v_mfma_f32_16x16x32_bf16 v[108:111], v[152:155], v[196:199], v[108:111]
	v_mfma_f32_16x16x32_bf16 v[104:107], v[160:163], v[196:199], v[104:107]
	v_mfma_f32_16x16x32_bf16 v[92:95], v[152:155], v[204:207], v[92:95]
	v_mfma_f32_16x16x32_bf16 v[88:91], v[160:163], v[204:207], v[88:91]
	v_mfma_f32_16x16x32_bf16 v[76:79], v[152:155], v[212:215], v[76:79]
	v_mfma_f32_16x16x32_bf16 v[72:75], v[160:163], v[212:215], v[72:75]
	s_setprio 0
	s_setprio 1
	v_mfma_f32_16x16x32_bf16 v[116:119], v[164:167], v[184:187], v[116:119]
	v_mfma_f32_16x16x32_bf16 v[112:115], v[172:175], v[184:187], v[112:115]
	v_mfma_f32_16x16x32_bf16 v[100:103], v[164:167], v[192:195], v[100:103]
	v_mfma_f32_16x16x32_bf16 v[96:99], v[172:175], v[192:195], v[96:99]
	v_mfma_f32_16x16x32_bf16 v[84:87], v[164:167], v[200:203], v[84:87]
	v_mfma_f32_16x16x32_bf16 v[80:83], v[172:175], v[200:203], v[80:83]
	v_mfma_f32_16x16x32_bf16 v[68:71], v[164:167], v[208:211], v[68:71]
	v_mfma_f32_16x16x32_bf16 v[64:67], v[172:175], v[208:211], v[64:67]
	v_mfma_f32_16x16x32_bf16 v[116:119], v[168:171], v[188:191], v[116:119]
	v_mfma_f32_16x16x32_bf16 v[112:115], v[180:183], v[188:191], v[112:115]
	v_mfma_f32_16x16x32_bf16 v[100:103], v[168:171], v[196:199], v[100:103]
	v_mfma_f32_16x16x32_bf16 v[96:99], v[180:183], v[196:199], v[96:99]
	v_mfma_f32_16x16x32_bf16 v[84:87], v[168:171], v[204:207], v[84:87]
	v_mfma_f32_16x16x32_bf16 v[80:83], v[180:183], v[204:207], v[80:83]
	v_mfma_f32_16x16x32_bf16 v[68:71], v[168:171], v[212:215], v[68:71]
	v_mfma_f32_16x16x32_bf16 v[64:67], v[180:183], v[212:215], v[64:67]
	s_setprio 0
	s_barrier
; #define PG8_BAR __builtin_amdgcn_s_barrier()
; template <class Epi>
; __device__ __forceinline__ void gemm_phase(LAS unsigned char* lds, const Gemm g, const StaticOrder& S, const Epi& E) {
;     ...
;         if (wr == 0) PG8_BAR;
	ds_read_b128 v[184:187], v150 offset:49152
	ds_read_b128 v[188:191], v150 offset:50176
	ds_read_b128 v[192:195], v150 offset:51200
	ds_read_b128 v[196:199], v150 offset:52224
	ds_read_b128 v[200:203], v150 offset:53248
	ds_read_b128 v[204:207], v150 offset:54272
	ds_read_b128 v[208:211], v150 offset:55296
	ds_read_b128 v[212:215], v150 offset:56320
	s_add_i32 s34, s75, s14
	v_lshl_add_u64 v[216:217], v[216:217], 0, s[20:21]
	s_mov_b32 m0, s34
	s_nop 0
	global_load_lds_dwordx4 v[216:217], off
	s_add_i32 m0, s34, 0x2000
	s_add_u32 s34, s62, 0x80080
	v_lshl_add_u64 v[216:217], v[218:219], 0, s[20:21]
	s_addc_u32 s35, s63, 0
	s_add_i32 s62, s76, s14
	global_load_lds_dwordx4 v[216:217], off
	v_lshl_add_u64 v[216:217], s[34:35], 0, v[130:131]
	s_mov_b32 m0, s62
	s_nop 0
	global_load_lds_dwordx4 v[216:217], off
	v_lshl_add_u64 v[216:217], s[34:35], 0, v[134:135]
	s_add_i32 m0, s62, 0x2000
	s_nop 0
	global_load_lds_dwordx4 v[216:217], off
	v_lshl_add_u64 v[216:217], v[222:223], 0, s[20:21]
	s_mov_b32 m0, s40
	s_nop 0
	global_load_lds_dwordx4 v[216:217], off
	v_lshl_add_u64 v[216:217], v[224:225], 0, s[20:21]
	s_mov_b32 m0, s41
	s_nop 0
	global_load_lds_dwordx4 v[216:217], off
	s_waitcnt vmcnt(8)
	s_waitcnt lgkmcnt(0)
	s_barrier
	s_setprio 1
	s_waitcnt lgkmcnt(0)
	v_mfma_f32_16x16x32_bf16 v[60:63], v[138:141], v[184:187], v[60:63]
	v_mfma_f32_16x16x32_bf16 v[56:59], v[156:159], v[184:187], v[56:59]
	v_mfma_f32_16x16x32_bf16 v[44:47], v[138:141], v[192:195], v[44:47]
	v_mfma_f32_16x16x32_bf16 v[40:43], v[156:159], v[192:195], v[40:43]
	v_mfma_f32_16x16x32_bf16 v[28:31], v[138:141], v[200:203], v[28:31]
	v_mfma_f32_16x16x32_bf16 v[24:27], v[156:159], v[200:203], v[24:27]
	v_mfma_f32_16x16x32_bf16 v[12:15], v[138:141], v[208:211], v[12:15]
	v_mfma_f32_16x16x32_bf16 v[8:11], v[156:159], v[208:211], v[8:11]
	v_mfma_f32_16x16x32_bf16 v[60:63], v[152:155], v[188:191], v[60:63]
	v_mfma_f32_16x16x32_bf16 v[56:59], v[160:163], v[188:191], v[56:59]
	v_mfma_f32_16x16x32_bf16 v[44:47], v[152:155], v[196:199], v[44:47]
	v_mfma_f32_16x16x32_bf16 v[40:43], v[160:163], v[196:199], v[40:43]
	v_mfma_f32_16x16x32_bf16 v[28:31], v[152:155], v[204:207], v[28:31]
	v_mfma_f32_16x16x32_bf16 v[24:27], v[160:163], v[204:207], v[24:27]
	v_mfma_f32_16x16x32_bf16 v[12:15], v[152:155], v[212:215], v[12:15]
	v_mfma_f32_16x16x32_bf16 v[8:11], v[160:163], v[212:215], v[8:11]
	s_setprio 0
	s_setprio 1
	v_mfma_f32_16x16x32_bf16 v[52:55], v[164:167], v[184:187], v[52:55]
	v_mfma_f32_16x16x32_bf16 v[48:51], v[172:175], v[184:187], v[48:51]
	v_mfma_f32_16x16x32_bf16 v[36:39], v[164:167], v[192:195], v[36:39]
	v_mfma_f32_16x16x32_bf16 v[32:35], v[172:175], v[192:195], v[32:35]
	v_mfma_f32_16x16x32_bf16 v[20:23], v[164:167], v[200:203], v[20:23]
	v_mfma_f32_16x16x32_bf16 v[16:19], v[172:175], v[200:203], v[16:19]
	v_mfma_f32_16x16x32_bf16 v[4:7], v[164:167], v[208:211], v[4:7]
	v_mfma_f32_16x16x32_bf16 v[0:3], v[172:175], v[208:211], v[0:3]
	v_mfma_f32_16x16x32_bf16 v[52:55], v[168:171], v[188:191], v[52:55]
	v_mfma_f32_16x16x32_bf16 v[48:51], v[180:183], v[188:191], v[48:51]
	v_mfma_f32_16x16x32_bf16 v[36:39], v[168:171], v[196:199], v[36:39]
	v_mfma_f32_16x16x32_bf16 v[32:35], v[180:183], v[196:199], v[32:35]
	v_mfma_f32_16x16x32_bf16 v[20:23], v[168:171], v[204:207], v[20:23]
	v_mfma_f32_16x16x32_bf16 v[16:19], v[180:183], v[204:207], v[16:19]
	v_mfma_f32_16x16x32_bf16 v[4:7], v[168:171], v[212:215], v[4:7]
	v_mfma_f32_16x16x32_bf16 v[0:3], v[180:183], v[212:215], v[0:3]
	s_setprio 0
	s_barrier
	s_add_i32 s74, s74, 2
	s_add_u32 s60, s60, 0x100
	s_addc_u32 s61, s61, 0
	s_add_u32 s72, s72, 0x100
	s_addc_u32 s73, s73, 0
	s_cmp_gt_u32 s74, 29
	s_cbranch_scc0 .LBB0_807
	s_and_b64 vcc, exec, s[26:27]
	s_cbranch_vccz .LBB0_810
	s_barrier

.LBB0_896:
	ds_read_b128 v[130:133], v230
	ds_read_b128 v[134:137], v230 offset:1024
	ds_read_b128 v[138:141], v230 offset:2048
	ds_read_b128 v[142:145], v230 offset:3072
	ds_read_b128 v[146:149], v231
	ds_read_b128 v[150:153], v231 offset:1024
	ds_read_b128 v[154:157], v231 offset:2048
	ds_read_b128 v[158:161], v231 offset:3072
	ds_read_b128 v[182:185], v232
	ds_read_b128 v[186:189], v232 offset:1024
	ds_read_b128 v[190:193], v232 offset:2048
	ds_read_b128 v[194:197], v232 offset:3072
	ds_read_b128 v[198:201], v232 offset:4096
	ds_read_b128 v[202:205], v232 offset:5120
	ds_read_b128 v[206:209], v232 offset:6144
	ds_read_b128 v[210:213], v232 offset:7168
	s_add_u32 s34, s10, 0xfff80080
	s_addc_u32 s35, s11, -1
	s_cmp_eq_u32 s73, 28
	s_cselect_b32 s77, s1, s35
	s_cselect_b32 s76, s9, s34
	s_cselect_b32 s75, s41, s72
	s_cselect_b32 s74, s65, s67
	v_lshl_add_u64 v[120:121], s[10:11], 0, v[170:171]
	s_add_i32 m0, s90, 0xc000
	s_nop 0
	global_load_lds_dwordx4 v[120:121], off
	v_lshl_add_u64 v[120:121], s[10:11], 0, v[172:173]
	s_add_i32 m0, s90, 0xe000
	s_nop 0
	global_load_lds_dwordx4 v[120:121], off
	s_waitcnt vmcnt(8)
	s_waitcnt lgkmcnt(0)
	s_barrier
	s_setprio 1
	s_waitcnt lgkmcnt(0)
	v_mfma_f32_16x16x32_bf16 v[126:129], v[130:133], v[182:185], v[126:129]
	v_mfma_f32_16x16x32_bf16 v[92:95], v[138:141], v[182:185], v[92:95]
	v_mfma_f32_16x16x32_bf16 v[108:111], v[130:133], v[190:193], v[108:111]
	v_mfma_f32_16x16x32_bf16 v[68:71], v[138:141], v[190:193], v[68:71]
	v_mfma_f32_16x16x32_bf16 v[100:103], v[130:133], v[198:201], v[100:103]
	v_mfma_f32_16x16x32_bf16 v[64:67], v[138:141], v[198:201], v[64:67]
	v_mfma_f32_16x16x32_bf16 v[116:119], v[130:133], v[206:209], v[116:119]
	v_mfma_f32_16x16x32_bf16 v[84:87], v[138:141], v[206:209], v[84:87]
	v_mfma_f32_16x16x32_bf16 v[126:129], v[134:137], v[186:189], v[126:129]
	v_mfma_f32_16x16x32_bf16 v[92:95], v[142:145], v[186:189], v[92:95]
	v_mfma_f32_16x16x32_bf16 v[108:111], v[134:137], v[194:197], v[108:111]
	v_mfma_f32_16x16x32_bf16 v[68:71], v[142:145], v[194:197], v[68:71]
	v_mfma_f32_16x16x32_bf16 v[100:103], v[134:137], v[202:205], v[100:103]
	v_mfma_f32_16x16x32_bf16 v[64:67], v[142:145], v[202:205], v[64:67]
	v_mfma_f32_16x16x32_bf16 v[116:119], v[134:137], v[210:213], v[116:119]
	v_mfma_f32_16x16x32_bf16 v[84:87], v[142:145], v[210:213], v[84:87]
	s_setprio 0
	s_setprio 1
	v_mfma_f32_16x16x32_bf16 v[120:123], v[146:149], v[182:185], v[122:125]
	v_mfma_f32_16x16x32_bf16 v[88:91], v[154:157], v[182:185], v[88:91]
	v_mfma_f32_16x16x32_bf16 v[104:107], v[146:149], v[190:193], v[104:107]
	v_mfma_f32_16x16x32_bf16 v[60:63], v[154:157], v[190:193], v[60:63]
	v_mfma_f32_16x16x32_bf16 v[96:99], v[146:149], v[198:201], v[96:99]
	v_mfma_f32_16x16x32_bf16 v[56:59], v[154:157], v[198:201], v[56:59]
	v_mfma_f32_16x16x32_bf16 v[112:115], v[146:149], v[206:209], v[112:115]
	v_mfma_f32_16x16x32_bf16 v[80:83], v[154:157], v[206:209], v[80:83]
	v_mfma_f32_16x16x32_bf16 v[120:123], v[150:153], v[186:189], v[120:123]
	v_mfma_f32_16x16x32_bf16 v[88:91], v[158:161], v[186:189], v[88:91]
	v_mfma_f32_16x16x32_bf16 v[104:107], v[150:153], v[194:197], v[104:107]
	v_mfma_f32_16x16x32_bf16 v[60:63], v[158:161], v[194:197], v[60:63]
	v_mfma_f32_16x16x32_bf16 v[96:99], v[150:153], v[202:205], v[96:99]
	v_mfma_f32_16x16x32_bf16 v[56:59], v[158:161], v[202:205], v[56:59]
	v_mfma_f32_16x16x32_bf16 v[112:115], v[150:153], v[210:213], v[112:115]
	v_mfma_f32_16x16x32_bf16 v[80:83], v[158:161], v[210:213], v[80:83]
	s_setprio 0
	s_barrier
	ds_read_b128 v[182:185], v232 offset:16384
	ds_read_b128 v[186:189], v232 offset:17408
	ds_read_b128 v[190:193], v232 offset:18432
	ds_read_b128 v[194:197], v232 offset:19456
	ds_read_b128 v[198:201], v232 offset:20480
	ds_read_b128 v[202:205], v232 offset:21504
	ds_read_b128 v[206:209], v232 offset:22528
	ds_read_b128 v[210:213], v232 offset:23552
	s_add_i32 s34, s37, s89
	v_lshl_add_u64 v[214:215], s[74:75], 0, v[164:165]
	s_mov_b32 m0, s34
	s_nop 0
	global_load_lds_dwordx4 v[214:215], off
	s_add_i32 m0, s34, 0x2000
	s_add_u32 s34, s74, 0x80000
	v_lshl_add_u64 v[216:217], s[74:75], 0, v[168:169]
	s_addc_u32 s35, s75, 0
	s_add_i32 s78, s38, s89
	global_load_lds_dwordx4 v[216:217], off
	v_lshl_add_u64 v[124:125], s[34:35], 0, v[164:165]
	s_mov_b32 m0, s78
	v_lshl_add_u64 v[218:219], s[76:77], 0, v[162:163]
	global_load_lds_dwordx4 v[124:125], off
	v_lshl_add_u64 v[124:125], s[34:35], 0, v[168:169]
	s_add_i32 m0, s78, 0x2000
	v_lshl_add_u64 v[234:235], s[76:77], 0, v[166:167]
	global_load_lds_dwordx4 v[124:125], off
	s_mov_b32 m0, s90
	s_nop 0
	global_load_lds_dwordx4 v[218:219], off
	s_mov_b32 m0, s91
	s_nop 0
	global_load_lds_dwordx4 v[234:235], off
	s_waitcnt vmcnt(8)
	s_waitcnt lgkmcnt(0)
	s_barrier
	s_setprio 1
	s_waitcnt lgkmcnt(0)
	v_mfma_f32_16x16x32_bf16 v[52:55], v[130:133], v[182:185], v[52:55]
	v_mfma_f32_16x16x32_bf16 v[20:23], v[138:141], v[182:185], v[20:23]
	v_mfma_f32_16x16x32_bf16 v[44:47], v[130:133], v[190:193], v[44:47]
	v_mfma_f32_16x16x32_bf16 v[16:19], v[138:141], v[190:193], v[16:19]
	v_mfma_f32_16x16x32_bf16 v[36:39], v[130:133], v[198:201], v[36:39]
	v_mfma_f32_16x16x32_bf16 v[12:15], v[138:141], v[198:201], v[12:15]
	v_mfma_f32_16x16x32_bf16 v[76:79], v[130:133], v[206:209], v[76:79]
	v_mfma_f32_16x16x32_bf16 v[28:31], v[138:141], v[206:209], v[28:31]
	v_mfma_f32_16x16x32_bf16 v[52:55], v[134:137], v[186:189], v[52:55]
	v_mfma_f32_16x16x32_bf16 v[20:23], v[142:145], v[186:189], v[20:23]
	v_mfma_f32_16x16x32_bf16 v[44:47], v[134:137], v[194:197], v[44:47]
	v_mfma_f32_16x16x32_bf16 v[16:19], v[142:145], v[194:197], v[16:19]
	v_mfma_f32_16x16x32_bf16 v[36:39], v[134:137], v[202:205], v[36:39]
	v_mfma_f32_16x16x32_bf16 v[12:15], v[142:145], v[202:205], v[12:15]
	v_mfma_f32_16x16x32_bf16 v[76:79], v[134:137], v[210:213], v[76:79]
	v_mfma_f32_16x16x32_bf16 v[28:31], v[142:145], v[210:213], v[28:31]
	s_setprio 0
	s_setprio 1
	v_mfma_f32_16x16x32_bf16 v[48:51], v[146:149], v[182:185], v[48:51]
	v_mfma_f32_16x16x32_bf16 v[8:11], v[154:157], v[182:185], v[8:11]
	v_mfma_f32_16x16x32_bf16 v[40:43], v[146:149], v[190:193], v[40:43]
	v_mfma_f32_16x16x32_bf16 v[4:7], v[154:157], v[190:193], v[4:7]
	v_mfma_f32_16x16x32_bf16 v[32:35], v[146:149], v[198:201], v[32:35]
	v_mfma_f32_16x16x32_bf16 v[0:3], v[154:157], v[198:201], v[0:3]
	v_mfma_f32_16x16x32_bf16 v[72:75], v[146:149], v[206:209], v[72:75]
	v_mfma_f32_16x16x32_bf16 v[24:27], v[154:157], v[206:209], v[24:27]
	v_mfma_f32_16x16x32_bf16 v[48:51], v[150:153], v[186:189], v[48:51]
	v_mfma_f32_16x16x32_bf16 v[8:11], v[158:161], v[186:189], v[8:11]
	v_mfma_f32_16x16x32_bf16 v[40:43], v[150:153], v[194:197], v[40:43]
	v_mfma_f32_16x16x32_bf16 v[4:7], v[158:161], v[194:197], v[4:7]
	v_mfma_f32_16x16x32_bf16 v[32:35], v[150:153], v[202:205], v[32:35]
	v_mfma_f32_16x16x32_bf16 v[0:3], v[158:161], v[202:205], v[0:3]
	v_mfma_f32_16x16x32_bf16 v[72:75], v[150:153], v[210:213], v[72:75]
	v_mfma_f32_16x16x32_bf16 v[24:27], v[158:161], v[210:213], v[24:27]
	s_setprio 0
	s_barrier
	s_add_i32 s78, 0, 0x18000
	v_add_u32_e32 v124, s78, v223
	s_add_i32 s79, 0, 0x1c000
	ds_read_b128 v[130:133], v124
	ds_read_b128 v[134:137], v124 offset:1024
	ds_read_b128 v[138:141], v124 offset:2048
	ds_read_b128 v[142:145], v124 offset:3072
	v_add_u32_e32 v124, s79, v223
	ds_read_b128 v[146:149], v124
	ds_read_b128 v[150:153], v124 offset:1024
	ds_read_b128 v[154:157], v124 offset:2048
	ds_read_b128 v[158:161], v124 offset:3072
	ds_read_b128 v[182:185], v232 offset:32768
	ds_read_b128 v[186:189], v232 offset:33792
	ds_read_b128 v[190:193], v232 offset:34816
	ds_read_b128 v[194:197], v232 offset:35840
	ds_read_b128 v[198:201], v232 offset:36864
	ds_read_b128 v[202:205], v232 offset:37888
	ds_read_b128 v[206:209], v232 offset:38912
	ds_read_b128 v[210:213], v232 offset:39936
	s_add_u32 s34, s76, 0x80000
	s_addc_u32 s35, s77, 0
	s_mov_b32 m0, s92
	v_lshl_add_u64 v[124:125], s[34:35], 0, v[162:163]
	global_load_lds_dwordx4 v[124:125], off
	v_lshl_add_u64 v[124:125], s[34:35], 0, v[166:167]
	s_mov_b32 m0, s93
	s_nop 0
	global_load_lds_dwordx4 v[124:125], off
	s_waitcnt vmcnt(8)
	s_waitcnt lgkmcnt(0)
	s_barrier
	s_setprio 1
	s_waitcnt lgkmcnt(0)
	v_mfma_f32_16x16x32_bf16 v[124:127], v[130:133], v[182:185], v[126:129]
	v_mfma_f32_16x16x32_bf16 v[92:95], v[138:141], v[182:185], v[92:95]
	v_mfma_f32_16x16x32_bf16 v[108:111], v[130:133], v[190:193], v[108:111]
	v_mfma_f32_16x16x32_bf16 v[68:71], v[138:141], v[190:193], v[68:71]
	v_mfma_f32_16x16x32_bf16 v[100:103], v[130:133], v[198:201], v[100:103]
	v_mfma_f32_16x16x32_bf16 v[64:67], v[138:141], v[198:201], v[64:67]
	v_mfma_f32_16x16x32_bf16 v[116:119], v[130:133], v[206:209], v[116:119]
	v_mfma_f32_16x16x32_bf16 v[84:87], v[138:141], v[206:209], v[84:87]
	v_mfma_f32_16x16x32_bf16 v[126:129], v[134:137], v[186:189], v[124:127]
	v_mfma_f32_16x16x32_bf16 v[92:95], v[142:145], v[186:189], v[92:95]
	v_mfma_f32_16x16x32_bf16 v[108:111], v[134:137], v[194:197], v[108:111]
	v_mfma_f32_16x16x32_bf16 v[68:71], v[142:145], v[194:197], v[68:71]
	v_mfma_f32_16x16x32_bf16 v[100:103], v[134:137], v[202:205], v[100:103]
	v_mfma_f32_16x16x32_bf16 v[64:67], v[142:145], v[202:205], v[64:67]
	v_mfma_f32_16x16x32_bf16 v[116:119], v[134:137], v[210:213], v[116:119]
	v_mfma_f32_16x16x32_bf16 v[84:87], v[142:145], v[210:213], v[84:87]
	s_setprio 0
	s_setprio 1
	v_mfma_f32_16x16x32_bf16 v[120:123], v[146:149], v[182:185], v[120:123]
	v_mfma_f32_16x16x32_bf16 v[88:91], v[154:157], v[182:185], v[88:91]
	v_mfma_f32_16x16x32_bf16 v[104:107], v[146:149], v[190:193], v[104:107]
	v_mfma_f32_16x16x32_bf16 v[60:63], v[154:157], v[190:193], v[60:63]
	v_mfma_f32_16x16x32_bf16 v[96:99], v[146:149], v[198:201], v[96:99]
	v_mfma_f32_16x16x32_bf16 v[56:59], v[154:157], v[198:201], v[56:59]
	v_mfma_f32_16x16x32_bf16 v[112:115], v[146:149], v[206:209], v[112:115]
	v_mfma_f32_16x16x32_bf16 v[80:83], v[154:157], v[206:209], v[80:83]
	v_mfma_f32_16x16x32_bf16 v[122:125], v[150:153], v[186:189], v[120:123]
	v_mfma_f32_16x16x32_bf16 v[88:91], v[158:161], v[186:189], v[88:91]
	v_mfma_f32_16x16x32_bf16 v[104:107], v[150:153], v[194:197], v[104:107]
	v_mfma_f32_16x16x32_bf16 v[60:63], v[158:161], v[194:197], v[60:63]
	v_mfma_f32_16x16x32_bf16 v[96:99], v[150:153], v[202:205], v[96:99]
	v_mfma_f32_16x16x32_bf16 v[56:59], v[158:161], v[202:205], v[56:59]
	v_mfma_f32_16x16x32_bf16 v[112:115], v[150:153], v[210:213], v[112:115]
	v_mfma_f32_16x16x32_bf16 v[80:83], v[158:161], v[210:213], v[80:83]
	s_setprio 0
	s_barrier
; #define PG8_BAR __builtin_amdgcn_s_barrier()
; template <class Epi>
; __device__ __forceinline__ void gemm_phase(LAS unsigned char* lds, const Gemm g, const StaticOrder& S, const Epi& E) {
;     ...
;         if (wr == 0) PG8_BAR;
	ds_read_b128 v[182:185], v232 offset:49152
	ds_read_b128 v[186:189], v232 offset:50176
	ds_read_b128 v[190:193], v232 offset:51200
	ds_read_b128 v[194:197], v232 offset:52224
	ds_read_b128 v[198:201], v232 offset:53248
	ds_read_b128 v[202:205], v232 offset:54272
	ds_read_b128 v[206:209], v232 offset:55296
	ds_read_b128 v[210:213], v232 offset:56320
	s_add_i32 s34, s78, s89
	v_lshl_add_u64 v[120:121], v[214:215], 0, s[50:51]
	s_mov_b32 m0, s34
	s_nop 0
	global_load_lds_dwordx4 v[120:121], off
	s_add_i32 m0, s34, 0x2000
	s_add_u32 s34, s74, 0x80080
	v_lshl_add_u64 v[120:121], v[216:217], 0, s[50:51]
	s_addc_u32 s35, s75, 0
	s_add_i32 s74, s79, s89
	global_load_lds_dwordx4 v[120:121], off
	v_lshl_add_u64 v[120:121], s[34:35], 0, v[164:165]
	s_mov_b32 m0, s74
	s_nop 0
	global_load_lds_dwordx4 v[120:121], off
	v_lshl_add_u64 v[120:121], s[34:35], 0, v[168:169]
	s_add_i32 m0, s74, 0x2000
	s_nop 0
	global_load_lds_dwordx4 v[120:121], off
	v_lshl_add_u64 v[120:121], v[218:219], 0, s[50:51]
	s_mov_b32 m0, s95
	s_nop 0
	global_load_lds_dwordx4 v[120:121], off
	v_lshl_add_u64 v[120:121], v[234:235], 0, s[50:51]
	s_mov_b32 m0, s96
	s_nop 0
	global_load_lds_dwordx4 v[120:121], off
	s_waitcnt vmcnt(8)
	s_waitcnt lgkmcnt(0)
	s_barrier
	s_setprio 1
	s_waitcnt lgkmcnt(0)
	v_mfma_f32_16x16x32_bf16 v[52:55], v[130:133], v[182:185], v[52:55]
	v_mfma_f32_16x16x32_bf16 v[20:23], v[138:141], v[182:185], v[20:23]
	v_mfma_f32_16x16x32_bf16 v[44:47], v[130:133], v[190:193], v[44:47]
	v_mfma_f32_16x16x32_bf16 v[16:19], v[138:141], v[190:193], v[16:19]
	v_mfma_f32_16x16x32_bf16 v[36:39], v[130:133], v[198:201], v[36:39]
	v_mfma_f32_16x16x32_bf16 v[12:15], v[138:141], v[198:201], v[12:15]
	v_mfma_f32_16x16x32_bf16 v[76:79], v[130:133], v[206:209], v[76:79]
	v_mfma_f32_16x16x32_bf16 v[28:31], v[138:141], v[206:209], v[28:31]
	v_mfma_f32_16x16x32_bf16 v[52:55], v[134:137], v[186:189], v[52:55]
	v_mfma_f32_16x16x32_bf16 v[20:23], v[142:145], v[186:189], v[20:23]
	v_mfma_f32_16x16x32_bf16 v[44:47], v[134:137], v[194:197], v[44:47]
	v_mfma_f32_16x16x32_bf16 v[16:19], v[142:145], v[194:197], v[16:19]
	v_mfma_f32_16x16x32_bf16 v[36:39], v[134:137], v[202:205], v[36:39]
	v_mfma_f32_16x16x32_bf16 v[12:15], v[142:145], v[202:205], v[12:15]
	v_mfma_f32_16x16x32_bf16 v[76:79], v[134:137], v[210:213], v[76:79]
	v_mfma_f32_16x16x32_bf16 v[28:31], v[142:145], v[210:213], v[28:31]
	s_setprio 0
	s_setprio 1
	v_mfma_f32_16x16x32_bf16 v[48:51], v[146:149], v[182:185], v[48:51]
	v_mfma_f32_16x16x32_bf16 v[8:11], v[154:157], v[182:185], v[8:11]
	v_mfma_f32_16x16x32_bf16 v[40:43], v[146:149], v[190:193], v[40:43]
	v_mfma_f32_16x16x32_bf16 v[4:7], v[154:157], v[190:193], v[4:7]
	v_mfma_f32_16x16x32_bf16 v[32:35], v[146:149], v[198:201], v[32:35]
	v_mfma_f32_16x16x32_bf16 v[0:3], v[154:157], v[198:201], v[0:3]
	v_mfma_f32_16x16x32_bf16 v[72:75], v[146:149], v[206:209], v[72:75]
	v_mfma_f32_16x16x32_bf16 v[24:27], v[154:157], v[206:209], v[24:27]
	v_mfma_f32_16x16x32_bf16 v[48:51], v[150:153], v[186:189], v[48:51]
	v_mfma_f32_16x16x32_bf16 v[8:11], v[158:161], v[186:189], v[8:11]
	v_mfma_f32_16x16x32_bf16 v[40:43], v[150:153], v[194:197], v[40:43]
	v_mfma_f32_16x16x32_bf16 v[4:7], v[158:161], v[194:197], v[4:7]
	v_mfma_f32_16x16x32_bf16 v[32:35], v[150:153], v[202:205], v[32:35]
	v_mfma_f32_16x16x32_bf16 v[0:3], v[158:161], v[202:205], v[0:3]
	v_mfma_f32_16x16x32_bf16 v[72:75], v[150:153], v[210:213], v[72:75]
	v_mfma_f32_16x16x32_bf16 v[24:27], v[158:161], v[210:213], v[24:27]
	s_setprio 0
	s_barrier
	s_add_i32 s73, s73, 2
	s_add_u32 s10, s10, 0x100
	s_addc_u32 s11, s11, 0
	s_add_u32 s67, s67, 0x100
	s_addc_u32 s72, s72, 0
	s_cmp_gt_u32 s73, 29
	s_cbranch_scc0 .LBB0_896
	s_and_b64 vcc, exec, s[52:53]
	s_cbranch_vccz .LBB0_899
	s_barrier

.LBB0_1128:
	ds_read_b128 v[128:131], v158
	ds_read_b128 v[132:135], v158 offset:1024
	ds_read_b128 v[146:149], v158 offset:2048
	ds_read_b128 v[162:165], v158 offset:3072
	ds_read_b128 v[166:169], v159
	ds_read_b128 v[170:173], v159 offset:1024
	ds_read_b128 v[180:183], v159 offset:2048
	ds_read_b128 v[184:187], v159 offset:3072
	ds_read_b128 v[188:191], v160
	ds_read_b128 v[192:195], v160 offset:1024
	ds_read_b128 v[196:199], v160 offset:2048
	ds_read_b128 v[200:203], v160 offset:3072
	ds_read_b128 v[204:207], v160 offset:4096
	ds_read_b128 v[208:211], v160 offset:5120
	ds_read_b128 v[212:215], v160 offset:6144
	ds_read_b128 v[216:219], v160 offset:7168
	s_add_u32 s34, s26, 0xffea0080
	s_addc_u32 s35, s27, -1
	s_cmpk_eq_i32 s56, 0x54
	s_cselect_b32 s43, s1, s35
	s_cselect_b32 s42, s0, s34
	s_cselect_b32 s39, s25, s55
	s_cselect_b32 s38, s24, s54
	v_lshl_add_u64 v[150:151], s[26:27], 0, v[136:137]
	s_add_i32 m0, s40, 0xc000
	s_nop 0
	global_load_lds_dwordx4 v[150:151], off
	v_lshl_add_u64 v[150:151], s[26:27], 0, v[140:141]
	s_add_i32 m0, s40, 0xe000
	s_nop 0
	global_load_lds_dwordx4 v[150:151], off
	s_waitcnt vmcnt(8)
	s_waitcnt lgkmcnt(0)
	s_barrier
	s_setprio 1
	s_waitcnt lgkmcnt(0)
	v_mfma_f32_16x16x32_bf16 v[76:79], v[128:131], v[188:191], v[76:79]
	v_mfma_f32_16x16x32_bf16 v[72:75], v[146:149], v[188:191], v[72:75]
	v_mfma_f32_16x16x32_bf16 v[124:127], v[128:131], v[196:199], v[124:127]
	v_mfma_f32_16x16x32_bf16 v[120:123], v[146:149], v[196:199], v[120:123]
	v_mfma_f32_16x16x32_bf16 v[116:119], v[128:131], v[204:207], v[116:119]
	v_mfma_f32_16x16x32_bf16 v[112:115], v[146:149], v[204:207], v[112:115]
	v_mfma_f32_16x16x32_bf16 v[96:99], v[128:131], v[212:215], v[96:99]
	v_mfma_f32_16x16x32_bf16 v[92:95], v[146:149], v[212:215], v[92:95]
	v_mfma_f32_16x16x32_bf16 v[76:79], v[132:135], v[192:195], v[76:79]
	v_mfma_f32_16x16x32_bf16 v[72:75], v[162:165], v[192:195], v[72:75]
	v_mfma_f32_16x16x32_bf16 v[124:127], v[132:135], v[200:203], v[124:127]
	v_mfma_f32_16x16x32_bf16 v[120:123], v[162:165], v[200:203], v[120:123]
	v_mfma_f32_16x16x32_bf16 v[116:119], v[132:135], v[208:211], v[116:119]
	v_mfma_f32_16x16x32_bf16 v[112:115], v[162:165], v[208:211], v[112:115]
	v_mfma_f32_16x16x32_bf16 v[96:99], v[132:135], v[216:219], v[96:99]
	v_mfma_f32_16x16x32_bf16 v[92:95], v[162:165], v[216:219], v[92:95]
	s_setprio 0
	s_setprio 1
	v_mfma_f32_16x16x32_bf16 v[68:71], v[166:169], v[188:191], v[68:71]
	v_mfma_f32_16x16x32_bf16 v[64:67], v[180:183], v[188:191], v[64:67]
	v_mfma_f32_16x16x32_bf16 v[108:111], v[166:169], v[196:199], v[108:111]
	v_mfma_f32_16x16x32_bf16 v[104:107], v[180:183], v[196:199], v[104:107]
	v_mfma_f32_16x16x32_bf16 v[100:103], v[166:169], v[204:207], v[100:103]
	v_mfma_f32_16x16x32_bf16 v[88:91], v[180:183], v[204:207], v[88:91]
	v_mfma_f32_16x16x32_bf16 v[84:87], v[166:169], v[212:215], v[84:87]
	v_mfma_f32_16x16x32_bf16 v[80:83], v[180:183], v[212:215], v[80:83]
	v_mfma_f32_16x16x32_bf16 v[68:71], v[170:173], v[192:195], v[68:71]
	v_mfma_f32_16x16x32_bf16 v[64:67], v[184:187], v[192:195], v[64:67]
	v_mfma_f32_16x16x32_bf16 v[108:111], v[170:173], v[200:203], v[108:111]
	v_mfma_f32_16x16x32_bf16 v[104:107], v[184:187], v[200:203], v[104:107]
	v_mfma_f32_16x16x32_bf16 v[100:103], v[170:173], v[208:211], v[100:103]
	v_mfma_f32_16x16x32_bf16 v[88:91], v[184:187], v[208:211], v[88:91]
	v_mfma_f32_16x16x32_bf16 v[84:87], v[170:173], v[216:219], v[84:87]
	v_mfma_f32_16x16x32_bf16 v[80:83], v[184:187], v[216:219], v[80:83]
	s_setprio 0
	s_barrier
	ds_read_b128 v[188:191], v160 offset:16384
	ds_read_b128 v[192:195], v160 offset:17408
	ds_read_b128 v[196:199], v160 offset:18432
	ds_read_b128 v[200:203], v160 offset:19456
	ds_read_b128 v[204:207], v160 offset:20480
	ds_read_b128 v[208:211], v160 offset:21504
	ds_read_b128 v[212:215], v160 offset:22528
	ds_read_b128 v[216:219], v160 offset:23552
	s_add_i32 s34, s8, s33
	v_lshl_add_u64 v[150:151], s[38:39], 0, v[138:139]
	s_mov_b32 m0, s34
	s_nop 0
	global_load_lds_dwordx4 v[150:151], off
	s_add_i32 m0, s34, 0x2000
	s_add_u32 s34, s38, 0x160000
	v_lshl_add_u64 v[174:175], s[38:39], 0, v[142:143]
	s_addc_u32 s35, s39, 0
	s_add_i32 s57, s49, s33
	global_load_lds_dwordx4 v[174:175], off
	v_lshl_add_u64 v[222:223], s[34:35], 0, v[138:139]
	s_mov_b32 m0, s57
	v_lshl_add_u64 v[224:225], s[42:43], 0, v[140:141]
	global_load_lds_dwordx4 v[222:223], off
	v_lshl_add_u64 v[222:223], s[34:35], 0, v[142:143]
	s_add_i32 m0, s57, 0x2000
	s_nop 0
	global_load_lds_dwordx4 v[222:223], off
	v_lshl_add_u64 v[222:223], s[42:43], 0, v[136:137]
	s_mov_b32 m0, s40
	s_nop 0
	global_load_lds_dwordx4 v[222:223], off
	s_mov_b32 m0, s41
	s_nop 0
	global_load_lds_dwordx4 v[224:225], off
	s_waitcnt vmcnt(8)
	s_waitcnt lgkmcnt(0)
	s_barrier
	s_setprio 1
	s_waitcnt lgkmcnt(0)
	v_mfma_f32_16x16x32_bf16 v[60:63], v[128:131], v[188:191], v[60:63]
	v_mfma_f32_16x16x32_bf16 v[56:59], v[146:149], v[188:191], v[56:59]
	v_mfma_f32_16x16x32_bf16 v[48:51], v[128:131], v[196:199], v[48:51]
	v_mfma_f32_16x16x32_bf16 v[40:43], v[146:149], v[196:199], v[40:43]
	v_mfma_f32_16x16x32_bf16 v[36:39], v[128:131], v[204:207], v[36:39]
	v_mfma_f32_16x16x32_bf16 v[28:31], v[146:149], v[204:207], v[28:31]
	v_mfma_f32_16x16x32_bf16 v[20:23], v[128:131], v[212:215], v[20:23]
	v_mfma_f32_16x16x32_bf16 v[12:15], v[146:149], v[212:215], v[12:15]
	v_mfma_f32_16x16x32_bf16 v[60:63], v[132:135], v[192:195], v[60:63]
	v_mfma_f32_16x16x32_bf16 v[56:59], v[162:165], v[192:195], v[56:59]
	v_mfma_f32_16x16x32_bf16 v[48:51], v[132:135], v[200:203], v[48:51]
	v_mfma_f32_16x16x32_bf16 v[40:43], v[162:165], v[200:203], v[40:43]
	v_mfma_f32_16x16x32_bf16 v[36:39], v[132:135], v[208:211], v[36:39]
	v_mfma_f32_16x16x32_bf16 v[28:31], v[162:165], v[208:211], v[28:31]
	v_mfma_f32_16x16x32_bf16 v[20:23], v[132:135], v[216:219], v[20:23]
	v_mfma_f32_16x16x32_bf16 v[12:15], v[162:165], v[216:219], v[12:15]
	s_setprio 0
	s_setprio 1
	v_mfma_f32_16x16x32_bf16 v[52:55], v[166:169], v[188:191], v[52:55]
	v_mfma_f32_16x16x32_bf16 v[44:47], v[180:183], v[188:191], v[44:47]
	v_mfma_f32_16x16x32_bf16 v[32:35], v[166:169], v[196:199], v[32:35]
	v_mfma_f32_16x16x32_bf16 v[24:27], v[180:183], v[196:199], v[24:27]
	v_mfma_f32_16x16x32_bf16 v[16:19], v[166:169], v[204:207], v[16:19]
	v_mfma_f32_16x16x32_bf16 v[8:11], v[180:183], v[204:207], v[8:11]
	v_mfma_f32_16x16x32_bf16 v[4:7], v[166:169], v[212:215], v[4:7]
	v_mfma_f32_16x16x32_bf16 v[0:3], v[180:183], v[212:215], v[0:3]
	v_mfma_f32_16x16x32_bf16 v[52:55], v[170:173], v[192:195], v[52:55]
	v_mfma_f32_16x16x32_bf16 v[44:47], v[184:187], v[192:195], v[44:47]
	v_mfma_f32_16x16x32_bf16 v[32:35], v[170:173], v[200:203], v[32:35]
	v_mfma_f32_16x16x32_bf16 v[24:27], v[184:187], v[200:203], v[24:27]
	v_mfma_f32_16x16x32_bf16 v[16:19], v[170:173], v[208:211], v[16:19]
	v_mfma_f32_16x16x32_bf16 v[8:11], v[184:187], v[208:211], v[8:11]
	v_mfma_f32_16x16x32_bf16 v[4:7], v[170:173], v[216:219], v[4:7]
	v_mfma_f32_16x16x32_bf16 v[0:3], v[184:187], v[216:219], v[0:3]
	s_setprio 0
	s_barrier
	s_add_i32 s57, 0, 0x18000
	v_add_u32_e32 v161, s57, v153
	s_add_i32 s58, 0, 0x1c000
	ds_read_b128 v[128:131], v161
	ds_read_b128 v[132:135], v161 offset:1024
	ds_read_b128 v[146:149], v161 offset:2048
	ds_read_b128 v[162:165], v161 offset:3072
	v_add_u32_e32 v161, s58, v153
	ds_read_b128 v[166:169], v161
	ds_read_b128 v[170:173], v161 offset:1024
	ds_read_b128 v[180:183], v161 offset:2048
	ds_read_b128 v[184:187], v161 offset:3072
	ds_read_b128 v[188:191], v160 offset:32768
	ds_read_b128 v[192:195], v160 offset:33792
	ds_read_b128 v[196:199], v160 offset:34816
	ds_read_b128 v[200:203], v160 offset:35840
	ds_read_b128 v[204:207], v160 offset:36864
	ds_read_b128 v[208:211], v160 offset:37888
	ds_read_b128 v[212:215], v160 offset:38912
	ds_read_b128 v[216:219], v160 offset:39936
	s_add_u32 s34, s42, 0x160000
	s_addc_u32 s35, s43, 0
	s_mov_b32 m0, s44
	v_lshl_add_u64 v[226:227], s[34:35], 0, v[136:137]
	global_load_lds_dwordx4 v[226:227], off
	v_lshl_add_u64 v[226:227], s[34:35], 0, v[140:141]
	s_mov_b32 m0, s45
	s_nop 0
	global_load_lds_dwordx4 v[226:227], off
	s_waitcnt vmcnt(8)
	s_waitcnt lgkmcnt(0)
	s_barrier
	s_setprio 1
	s_waitcnt lgkmcnt(0)
	v_mfma_f32_16x16x32_bf16 v[76:79], v[128:131], v[188:191], v[76:79]
	v_mfma_f32_16x16x32_bf16 v[72:75], v[146:149], v[188:191], v[72:75]
	v_mfma_f32_16x16x32_bf16 v[124:127], v[128:131], v[196:199], v[124:127]
	v_mfma_f32_16x16x32_bf16 v[120:123], v[146:149], v[196:199], v[120:123]
	v_mfma_f32_16x16x32_bf16 v[116:119], v[128:131], v[204:207], v[116:119]
	v_mfma_f32_16x16x32_bf16 v[112:115], v[146:149], v[204:207], v[112:115]
	v_mfma_f32_16x16x32_bf16 v[96:99], v[128:131], v[212:215], v[96:99]
	v_mfma_f32_16x16x32_bf16 v[92:95], v[146:149], v[212:215], v[92:95]
	v_mfma_f32_16x16x32_bf16 v[76:79], v[132:135], v[192:195], v[76:79]
	v_mfma_f32_16x16x32_bf16 v[72:75], v[162:165], v[192:195], v[72:75]
	v_mfma_f32_16x16x32_bf16 v[124:127], v[132:135], v[200:203], v[124:127]
	v_mfma_f32_16x16x32_bf16 v[120:123], v[162:165], v[200:203], v[120:123]
	v_mfma_f32_16x16x32_bf16 v[116:119], v[132:135], v[208:211], v[116:119]
	v_mfma_f32_16x16x32_bf16 v[112:115], v[162:165], v[208:211], v[112:115]
	v_mfma_f32_16x16x32_bf16 v[96:99], v[132:135], v[216:219], v[96:99]
	v_mfma_f32_16x16x32_bf16 v[92:95], v[162:165], v[216:219], v[92:95]
	s_setprio 0
	s_setprio 1
	v_mfma_f32_16x16x32_bf16 v[68:71], v[166:169], v[188:191], v[68:71]
	v_mfma_f32_16x16x32_bf16 v[64:67], v[180:183], v[188:191], v[64:67]
	v_mfma_f32_16x16x32_bf16 v[108:111], v[166:169], v[196:199], v[108:111]
	v_mfma_f32_16x16x32_bf16 v[104:107], v[180:183], v[196:199], v[104:107]
	v_mfma_f32_16x16x32_bf16 v[100:103], v[166:169], v[204:207], v[100:103]
	v_mfma_f32_16x16x32_bf16 v[88:91], v[180:183], v[204:207], v[88:91]
	v_mfma_f32_16x16x32_bf16 v[84:87], v[166:169], v[212:215], v[84:87]
	v_mfma_f32_16x16x32_bf16 v[80:83], v[180:183], v[212:215], v[80:83]
	v_mfma_f32_16x16x32_bf16 v[68:71], v[170:173], v[192:195], v[68:71]
	v_mfma_f32_16x16x32_bf16 v[64:67], v[184:187], v[192:195], v[64:67]
	v_mfma_f32_16x16x32_bf16 v[108:111], v[170:173], v[200:203], v[108:111]
	v_mfma_f32_16x16x32_bf16 v[104:107], v[184:187], v[200:203], v[104:107]
	v_mfma_f32_16x16x32_bf16 v[100:103], v[170:173], v[208:211], v[100:103]
	v_mfma_f32_16x16x32_bf16 v[88:91], v[184:187], v[208:211], v[88:91]
	v_mfma_f32_16x16x32_bf16 v[84:87], v[170:173], v[216:219], v[84:87]
	v_mfma_f32_16x16x32_bf16 v[80:83], v[184:187], v[216:219], v[80:83]
	s_setprio 0
	s_barrier
; #define PG8_BAR __builtin_amdgcn_s_barrier()
; template <class Epi>
; __device__ __forceinline__ void gemm_phase(LAS unsigned char* lds, const Gemm g, const StaticOrder& S, const Epi& E) {
;     ...
;         if (wr == 0) PG8_BAR;
	ds_read_b128 v[188:191], v160 offset:49152
	ds_read_b128 v[192:195], v160 offset:50176
	ds_read_b128 v[196:199], v160 offset:51200
	ds_read_b128 v[200:203], v160 offset:52224
	ds_read_b128 v[204:207], v160 offset:53248
	ds_read_b128 v[208:211], v160 offset:54272
	ds_read_b128 v[212:215], v160 offset:55296
	ds_read_b128 v[216:219], v160 offset:56320
	s_add_i32 s34, s57, s33
	v_lshl_add_u64 v[150:151], v[150:151], 0, s[14:15]
	s_mov_b32 m0, s34
	s_nop 0
	global_load_lds_dwordx4 v[150:151], off
	s_add_i32 m0, s34, 0x2000
	s_add_u32 s34, s38, 0x160080
	v_lshl_add_u64 v[150:151], v[174:175], 0, s[14:15]
	s_addc_u32 s35, s39, 0
	s_add_i32 s38, s58, s33
	global_load_lds_dwordx4 v[150:151], off
	v_lshl_add_u64 v[150:151], s[34:35], 0, v[138:139]
	s_mov_b32 m0, s38
	s_nop 0
	global_load_lds_dwordx4 v[150:151], off
	v_lshl_add_u64 v[150:151], s[34:35], 0, v[142:143]
	s_add_i32 m0, s38, 0x2000
	s_nop 0
	global_load_lds_dwordx4 v[150:151], off
	v_lshl_add_u64 v[150:151], v[222:223], 0, s[14:15]
	s_mov_b32 m0, s46
	s_nop 0
	global_load_lds_dwordx4 v[150:151], off
	v_lshl_add_u64 v[150:151], v[224:225], 0, s[14:15]
	s_mov_b32 m0, s47
	s_nop 0
	global_load_lds_dwordx4 v[150:151], off
	s_waitcnt vmcnt(8)
	s_waitcnt lgkmcnt(0)
	s_barrier
	s_setprio 1
	s_waitcnt lgkmcnt(0)
	v_mfma_f32_16x16x32_bf16 v[60:63], v[128:131], v[188:191], v[60:63]
	v_mfma_f32_16x16x32_bf16 v[56:59], v[146:149], v[188:191], v[56:59]
	v_mfma_f32_16x16x32_bf16 v[48:51], v[128:131], v[196:199], v[48:51]
	v_mfma_f32_16x16x32_bf16 v[40:43], v[146:149], v[196:199], v[40:43]
	v_mfma_f32_16x16x32_bf16 v[36:39], v[128:131], v[204:207], v[36:39]
	v_mfma_f32_16x16x32_bf16 v[28:31], v[146:149], v[204:207], v[28:31]
	v_mfma_f32_16x16x32_bf16 v[20:23], v[128:131], v[212:215], v[20:23]
	v_mfma_f32_16x16x32_bf16 v[12:15], v[146:149], v[212:215], v[12:15]
	v_mfma_f32_16x16x32_bf16 v[60:63], v[132:135], v[192:195], v[60:63]
	v_mfma_f32_16x16x32_bf16 v[56:59], v[162:165], v[192:195], v[56:59]
	v_mfma_f32_16x16x32_bf16 v[48:51], v[132:135], v[200:203], v[48:51]
	v_mfma_f32_16x16x32_bf16 v[40:43], v[162:165], v[200:203], v[40:43]
	v_mfma_f32_16x16x32_bf16 v[36:39], v[132:135], v[208:211], v[36:39]
	v_mfma_f32_16x16x32_bf16 v[28:31], v[162:165], v[208:211], v[28:31]
	v_mfma_f32_16x16x32_bf16 v[20:23], v[132:135], v[216:219], v[20:23]
	v_mfma_f32_16x16x32_bf16 v[12:15], v[162:165], v[216:219], v[12:15]
	s_setprio 0
	s_setprio 1
	v_mfma_f32_16x16x32_bf16 v[52:55], v[166:169], v[188:191], v[52:55]
	v_mfma_f32_16x16x32_bf16 v[44:47], v[180:183], v[188:191], v[44:47]
	v_mfma_f32_16x16x32_bf16 v[32:35], v[166:169], v[196:199], v[32:35]
	v_mfma_f32_16x16x32_bf16 v[24:27], v[180:183], v[196:199], v[24:27]
	v_mfma_f32_16x16x32_bf16 v[16:19], v[166:169], v[204:207], v[16:19]
	v_mfma_f32_16x16x32_bf16 v[8:11], v[180:183], v[204:207], v[8:11]
	v_mfma_f32_16x16x32_bf16 v[4:7], v[166:169], v[212:215], v[4:7]
	v_mfma_f32_16x16x32_bf16 v[0:3], v[180:183], v[212:215], v[0:3]
	v_mfma_f32_16x16x32_bf16 v[52:55], v[170:173], v[192:195], v[52:55]
	v_mfma_f32_16x16x32_bf16 v[44:47], v[184:187], v[192:195], v[44:47]
	v_mfma_f32_16x16x32_bf16 v[32:35], v[170:173], v[200:203], v[32:35]
	v_mfma_f32_16x16x32_bf16 v[24:27], v[184:187], v[200:203], v[24:27]
	v_mfma_f32_16x16x32_bf16 v[16:19], v[170:173], v[208:211], v[16:19]
	v_mfma_f32_16x16x32_bf16 v[8:11], v[184:187], v[208:211], v[8:11]
	v_mfma_f32_16x16x32_bf16 v[4:7], v[170:173], v[216:219], v[4:7]
	v_mfma_f32_16x16x32_bf16 v[0:3], v[184:187], v[216:219], v[0:3]
	s_setprio 0
	s_barrier
	s_add_i32 s56, s56, 2
	s_add_u32 s26, s26, 0x100
	s_addc_u32 s27, s27, 0
	s_add_u32 s54, s54, 0x100
	s_addc_u32 s55, s55, 0
	s_cmpk_gt_u32 s56, 0x55
	s_cbranch_scc0 .LBB0_1128
	s_and_b64 vcc, exec, s[22:23]
	s_cbranch_vccz .LBB0_1131
	s_barrier
